# all skinny split-K reduce loops batch their LDS reads; up-projection epilogues issue the 8 per-row norm loads together; residual-row pre-touch also on the non-piped skinny path
# speedup vs baseline: 1.0692x; 1.0051x over previous
; __device__ __forceinline__ float sum4(f32x4 v) { return (v.x + v.y) + (v.z + v.w); }
;     template <int A0, int A1> __device__ __forceinline__ void run(const f32x4 (&acc)[2][2][4][2], const Unit& u, int wr, int wc, int fr, int fq) const {
;         const int lpn = u.pn + pn_off;
;         const bool isq = lpn < 3;
;         const int row0 = u.pm * 256 + wr * 64 + fr;
; #pragma unroll
;         for (int ai = A0; ai < A1; ++ai)
; #pragma unroll
;             for (int m = 0; m < 4; ++m) {
;                 const int row = row0 + ai * 128 + m * 16;
;                 const f32x4 pv = isq ? *(const f32x4*)(ssqq + (size_t)row * 4) : *(const f32x4*)(ssqkv + (size_t)row * 4);
;                 const float rr = isq ? rsqrtf(sum4(pv) * (1.0f / 256.0f) + EPS) * C2 : rsqrtf(sum4(pv) * (1.0f / 128.0f) + EPS);
.LBB0_421:
	s_cmp_gt_i32 s24, 2
	s_cselect_b64 s[38:39], -1, 0
	s_lshl_b32 s14, s84, 8
	s_add_i32 s14, s14, s26
	s_cmp_lt_i32 s24, 3
	s_cselect_b64 s[10:11], -1, 0
	v_or_b32_e32 v140, s14, v139
	s_and_b64 s[8:9], s[10:11], exec
	v_ashrrev_i32_e32 v141, 31, v140
	s_cselect_b32 s37, s44, s83
	s_cselect_b32 s36, s75, s82
	v_lshl_add_u64 v[142:143], v[140:141], 4, s[36:37]
	global_load_dwordx4 v[220:223], v[142:143], off offset:256
	global_load_dwordx4 v[224:227], v[142:143], off offset:512
	global_load_dwordx4 v[228:231], v[142:143], off offset:768
	global_load_dwordx4 v[232:235], v[142:143], off offset:2048
	global_load_dwordx4 v[240:243], v[142:143], off offset:2304
	global_load_dwordx4 v[244:247], v[142:143], off offset:2560
	global_load_dwordx4 v[248:251], v[142:143], off offset:2816
	global_load_dwordx4 v[144:147], v[142:143], off
	s_mov_b64 s[8:9], -1
	s_and_b64 vcc, exec, s[38:39]
	s_waitcnt vmcnt(0)
	v_add_f32_e32 v128, v144, v145
	v_add_f32_e32 v143, v146, v147
	v_add_f32_e32 v128, v128, v143
	s_cbranch_vccz .LBB0_423
	v_fmamk_f32 v142, v128, 0x3c000000, v252
	v_mul_f32_e32 v143, 0x4b800000, v142
	v_cmp_gt_f32_e32 vcc, s49, v142
	s_mov_b64 s[8:9], 0
	s_nop 0
	v_cndmask_b32_e32 v142, v142, v143, vcc
	v_rsq_f32_e32 v142, v142
	s_nop 0
	v_mul_f32_e32 v143, 0x45800000, v142
	v_cndmask_b32_e32 v142, v142, v143, vcc

; __device__ __forceinline__ unsigned cvt_pk_bf16(float lo, float hi) { const f32x2 v = {lo, hi}; return __builtin_bit_cast(unsigned, __builtin_convertvector(v, bf16x2_t)); }
; __device__ __forceinline__ float sum4(f32x4 v) { return (v.x + v.y) + (v.z + v.w); }
;     template <int A0, int A1> __device__ __forceinline__ void run(const f32x4 (&acc)[2][2][4][2], const Unit& u, int wr, int wc, int fr, int fq) const {
;     ...
;             for (int m = 0; m < 4; ++m) {
;                 const int row = row0 + ai * 128 + m * 16;
;                 const f32x4 pv = isq ? *(const f32x4*)(ssqq + (size_t)row * 4) : *(const f32x4*)(ssqkv + (size_t)row * 4);
;                 const float rr = isq ? rsqrtf(sum4(pv) * (1.0f / 256.0f) + EPS) * C2 : rsqrtf(sum4(pv) * (1.0f / 128.0f) + EPS);
; #pragma unroll
;                 for (int bj = 0; bj < 2; ++bj) {
;                     const int cbase = lpn * 256 + bj * 128 + wc * 32;
;                     f32x4 v0 = acc[ai][bj][m][0] * rr, v1 = acc[ai][bj][m][1] * rr;
;                     if (isq && ((cbase >> 5) % 3) == 2 && u.pm < 64) rope_apply(v0, v1, rope, row, fq);
;                     u32x4 w; w.x = cvt_pk_bf16(v0.x, v0.y); w.y = cvt_pk_bf16(v0.z, v0.w); w.z = cvt_pk_bf16(v1.x, v1.y); w.w = cvt_pk_bf16(v1.z, v1.w);
;                     if (isq) *(u32x4*)(Q + (size_t)row * 768 + cbase + fq * 8) = w;
.LBB0_439:
	v_cvt_pk_bf16_f32 v116, v116, v117
	v_cvt_pk_bf16_f32 v117, v118, v119
	v_cvt_pk_bf16_f32 v119, v114, v115
	v_or_b32_e32 v114, 16, v140
	v_cvt_pk_bf16_f32 v118, v112, v113
	v_lshl_add_u64 v[112:113], v[124:125], 0, v[128:129]
	v_ashrrev_i32_e32 v115, 31, v114
	global_store_dwordx4 v[112:113], v[116:119], off
	v_lshl_add_u64 v[112:113], v[114:115], 4, s[36:37]
	s_nop 1
	v_mov_b64_e32 v[116:117], v[220:221]
	v_mov_b64_e32 v[118:119], v[222:223]
	s_and_b64 vcc, exec, s[10:11]
	s_mov_b64 s[20:21], -1
	s_waitcnt vmcnt(0)
	v_add_f32_e32 v112, v116, v117
	v_add_f32_e32 v113, v118, v119
	v_add_f32_e32 v113, v112, v113
	s_cbranch_vccnz .LBB0_441
	v_fmamk_f32 v112, v113, 0x3c000000, v252
	v_mul_f32_e32 v116, 0x4b800000, v112
	v_cmp_gt_f32_e32 vcc, s49, v112
	s_mov_b64 s[20:21], 0
	s_nop 0
	v_cndmask_b32_e32 v112, v112, v116, vcc
	v_rsq_f32_e32 v112, v112
	s_nop 0
	v_mul_f32_e32 v116, 0x45800000, v112
	v_cndmask_b32_e32 v112, v112, v116, vcc

; __device__ __forceinline__ unsigned cvt_pk_bf16(float lo, float hi) { const f32x2 v = {lo, hi}; return __builtin_bit_cast(unsigned, __builtin_convertvector(v, bf16x2_t)); }
; __device__ __forceinline__ float sum4(f32x4 v) { return (v.x + v.y) + (v.z + v.w); }
;     template <int A0, int A1> __device__ __forceinline__ void run(const f32x4 (&acc)[2][2][4][2], const Unit& u, int wr, int wc, int fr, int fq) const {
;     ...
;             for (int m = 0; m < 4; ++m) {
;                 const int row = row0 + ai * 128 + m * 16;
;                 const f32x4 pv = isq ? *(const f32x4*)(ssqq + (size_t)row * 4) : *(const f32x4*)(ssqkv + (size_t)row * 4);
;                 const float rr = isq ? rsqrtf(sum4(pv) * (1.0f / 256.0f) + EPS) * C2 : rsqrtf(sum4(pv) * (1.0f / 128.0f) + EPS);
; #pragma unroll
;                 for (int bj = 0; bj < 2; ++bj) {
;                     const int cbase = lpn * 256 + bj * 128 + wc * 32;
;                     f32x4 v0 = acc[ai][bj][m][0] * rr, v1 = acc[ai][bj][m][1] * rr;
;                     if (isq && ((cbase >> 5) % 3) == 2 && u.pm < 64) rope_apply(v0, v1, rope, row, fq);
;                     u32x4 w; w.x = cvt_pk_bf16(v0.x, v0.y); w.y = cvt_pk_bf16(v0.z, v0.w); w.z = cvt_pk_bf16(v1.x, v1.y); w.w = cvt_pk_bf16(v1.z, v1.w);
;                     if (isq) *(u32x4*)(Q + (size_t)row * 768 + cbase + fq * 8) = w;
.LBB0_457:
	v_cvt_pk_bf16_f32 v100, v100, v101
	v_cvt_pk_bf16_f32 v101, v102, v103
	v_cvt_pk_bf16_f32 v103, v98, v99
	v_or_b32_e32 v98, 32, v140
	v_cvt_pk_bf16_f32 v102, v96, v97
	v_lshl_add_u64 v[96:97], v[108:109], 0, v[128:129]
	v_ashrrev_i32_e32 v99, 31, v98
	global_store_dwordx4 v[96:97], v[100:103], off
	v_lshl_add_u64 v[96:97], v[98:99], 4, s[36:37]
	s_nop 1
	v_mov_b64_e32 v[100:101], v[224:225]
	v_mov_b64_e32 v[102:103], v[226:227]
	s_and_b64 vcc, exec, s[10:11]
	s_mov_b64 s[20:21], -1
	s_waitcnt vmcnt(0)
	v_add_f32_e32 v96, v100, v101
	v_add_f32_e32 v97, v102, v103
	v_add_f32_e32 v97, v96, v97
	s_cbranch_vccnz .LBB0_459
	v_fmamk_f32 v96, v97, 0x3c000000, v252
	v_mul_f32_e32 v100, 0x4b800000, v96
	v_cmp_gt_f32_e32 vcc, s49, v96
	s_mov_b64 s[20:21], 0
	s_nop 0
	v_cndmask_b32_e32 v96, v96, v100, vcc
	v_rsq_f32_e32 v96, v96
	s_nop 0
	v_mul_f32_e32 v100, 0x45800000, v96
	v_cndmask_b32_e32 v96, v96, v100, vcc

; __device__ __forceinline__ unsigned cvt_pk_bf16(float lo, float hi) { const f32x2 v = {lo, hi}; return __builtin_bit_cast(unsigned, __builtin_convertvector(v, bf16x2_t)); }
; __device__ __forceinline__ float sum4(f32x4 v) { return (v.x + v.y) + (v.z + v.w); }
;     template <int A0, int A1> __device__ __forceinline__ void run(const f32x4 (&acc)[2][2][4][2], const Unit& u, int wr, int wc, int fr, int fq) const {
;     ...
;             for (int m = 0; m < 4; ++m) {
;                 const int row = row0 + ai * 128 + m * 16;
;                 const f32x4 pv = isq ? *(const f32x4*)(ssqq + (size_t)row * 4) : *(const f32x4*)(ssqkv + (size_t)row * 4);
;                 const float rr = isq ? rsqrtf(sum4(pv) * (1.0f / 256.0f) + EPS) * C2 : rsqrtf(sum4(pv) * (1.0f / 128.0f) + EPS);
; #pragma unroll
;                 for (int bj = 0; bj < 2; ++bj) {
;                     const int cbase = lpn * 256 + bj * 128 + wc * 32;
;                     f32x4 v0 = acc[ai][bj][m][0] * rr, v1 = acc[ai][bj][m][1] * rr;
;                     if (isq && ((cbase >> 5) % 3) == 2 && u.pm < 64) rope_apply(v0, v1, rope, row, fq);
;                     u32x4 w; w.x = cvt_pk_bf16(v0.x, v0.y); w.y = cvt_pk_bf16(v0.z, v0.w); w.z = cvt_pk_bf16(v1.x, v1.y); w.w = cvt_pk_bf16(v1.z, v1.w);
;                     if (isq) *(u32x4*)(Q + (size_t)row * 768 + cbase + fq * 8) = w;
.LBB0_475:
	v_cvt_pk_bf16_f32 v84, v84, v85
	v_cvt_pk_bf16_f32 v85, v86, v87
	v_cvt_pk_bf16_f32 v87, v82, v83
	v_or_b32_e32 v82, 48, v140
	v_cvt_pk_bf16_f32 v86, v80, v81
	v_lshl_add_u64 v[80:81], v[92:93], 0, v[128:129]
	v_ashrrev_i32_e32 v83, 31, v82
	global_store_dwordx4 v[80:81], v[84:87], off
	v_lshl_add_u64 v[80:81], v[82:83], 4, s[36:37]
	s_nop 1
	v_mov_b64_e32 v[84:85], v[228:229]
	v_mov_b64_e32 v[86:87], v[230:231]
	s_and_b64 vcc, exec, s[10:11]
	s_mov_b64 s[20:21], -1
	s_waitcnt vmcnt(0)
	v_add_f32_e32 v80, v84, v85
	v_add_f32_e32 v81, v86, v87
	v_add_f32_e32 v81, v80, v81
	s_cbranch_vccnz .LBB0_477
	v_fmamk_f32 v80, v81, 0x3c000000, v252
	v_mul_f32_e32 v84, 0x4b800000, v80
	v_cmp_gt_f32_e32 vcc, s49, v80
	s_mov_b64 s[20:21], 0
	s_nop 0
	v_cndmask_b32_e32 v80, v80, v84, vcc
	v_rsq_f32_e32 v80, v80
	s_nop 0
	v_mul_f32_e32 v84, 0x45800000, v80
	v_cndmask_b32_e32 v80, v80, v84, vcc

; __device__ __forceinline__ unsigned cvt_pk_bf16(float lo, float hi) { const f32x2 v = {lo, hi}; return __builtin_bit_cast(unsigned, __builtin_convertvector(v, bf16x2_t)); }
; __device__ __forceinline__ float sum4(f32x4 v) { return (v.x + v.y) + (v.z + v.w); }
;     template <int A0, int A1> __device__ __forceinline__ void run(const f32x4 (&acc)[2][2][4][2], const Unit& u, int wr, int wc, int fr, int fq) const {
;     ...
;             for (int m = 0; m < 4; ++m) {
;                 const int row = row0 + ai * 128 + m * 16;
;                 const f32x4 pv = isq ? *(const f32x4*)(ssqq + (size_t)row * 4) : *(const f32x4*)(ssqkv + (size_t)row * 4);
;                 const float rr = isq ? rsqrtf(sum4(pv) * (1.0f / 256.0f) + EPS) * C2 : rsqrtf(sum4(pv) * (1.0f / 128.0f) + EPS);
; #pragma unroll
;                 for (int bj = 0; bj < 2; ++bj) {
;                     const int cbase = lpn * 256 + bj * 128 + wc * 32;
;                     f32x4 v0 = acc[ai][bj][m][0] * rr, v1 = acc[ai][bj][m][1] * rr;
;                     if (isq && ((cbase >> 5) % 3) == 2 && u.pm < 64) rope_apply(v0, v1, rope, row, fq);
;                     u32x4 w; w.x = cvt_pk_bf16(v0.x, v0.y); w.y = cvt_pk_bf16(v0.z, v0.w); w.z = cvt_pk_bf16(v1.x, v1.y); w.w = cvt_pk_bf16(v1.z, v1.w);
;                     if (isq) *(u32x4*)(Q + (size_t)row * 768 + cbase + fq * 8) = w;
.LBB0_493:
	v_cvt_pk_bf16_f32 v68, v68, v69
	v_cvt_pk_bf16_f32 v69, v70, v71
	v_cvt_pk_bf16_f32 v71, v66, v67
	v_add_u32_e32 v66, 0x80, v140
	v_cvt_pk_bf16_f32 v70, v64, v65
	v_lshl_add_u64 v[64:65], v[76:77], 0, v[128:129]
	v_ashrrev_i32_e32 v67, 31, v66
	global_store_dwordx4 v[64:65], v[68:71], off
	v_lshl_add_u64 v[64:65], v[66:67], 4, s[36:37]
	s_nop 1
	v_mov_b64_e32 v[68:69], v[232:233]
	v_mov_b64_e32 v[70:71], v[234:235]
	s_and_b64 vcc, exec, s[10:11]
	s_mov_b64 s[20:21], -1
	s_waitcnt vmcnt(0)
	v_add_f32_e32 v64, v68, v69
	v_add_f32_e32 v65, v70, v71
	v_add_f32_e32 v65, v64, v65
	s_cbranch_vccnz .LBB0_495
	v_fmamk_f32 v64, v65, 0x3c000000, v252
	v_mul_f32_e32 v68, 0x4b800000, v64
	v_cmp_gt_f32_e32 vcc, s49, v64
	s_mov_b64 s[20:21], 0
	s_nop 0
	v_cndmask_b32_e32 v64, v64, v68, vcc
	v_rsq_f32_e32 v64, v64
	s_nop 0
	v_mul_f32_e32 v68, 0x45800000, v64
	v_cndmask_b32_e32 v64, v64, v68, vcc

; __device__ __forceinline__ unsigned cvt_pk_bf16(float lo, float hi) { const f32x2 v = {lo, hi}; return __builtin_bit_cast(unsigned, __builtin_convertvector(v, bf16x2_t)); }
; __device__ __forceinline__ float sum4(f32x4 v) { return (v.x + v.y) + (v.z + v.w); }
;     template <int A0, int A1> __device__ __forceinline__ void run(const f32x4 (&acc)[2][2][4][2], const Unit& u, int wr, int wc, int fr, int fq) const {
;     ...
;             for (int m = 0; m < 4; ++m) {
;                 const int row = row0 + ai * 128 + m * 16;
;                 const f32x4 pv = isq ? *(const f32x4*)(ssqq + (size_t)row * 4) : *(const f32x4*)(ssqkv + (size_t)row * 4);
;                 const float rr = isq ? rsqrtf(sum4(pv) * (1.0f / 256.0f) + EPS) * C2 : rsqrtf(sum4(pv) * (1.0f / 128.0f) + EPS);
; #pragma unroll
;                 for (int bj = 0; bj < 2; ++bj) {
;                     const int cbase = lpn * 256 + bj * 128 + wc * 32;
;                     f32x4 v0 = acc[ai][bj][m][0] * rr, v1 = acc[ai][bj][m][1] * rr;
;                     if (isq && ((cbase >> 5) % 3) == 2 && u.pm < 64) rope_apply(v0, v1, rope, row, fq);
;                     u32x4 w; w.x = cvt_pk_bf16(v0.x, v0.y); w.y = cvt_pk_bf16(v0.z, v0.w); w.z = cvt_pk_bf16(v1.x, v1.y); w.w = cvt_pk_bf16(v1.z, v1.w);
;                     if (isq) *(u32x4*)(Q + (size_t)row * 768 + cbase + fq * 8) = w;
.LBB0_511:
	v_cvt_pk_bf16_f32 v52, v52, v53
	v_cvt_pk_bf16_f32 v53, v54, v55
	v_cvt_pk_bf16_f32 v55, v50, v51
	v_add_u32_e32 v50, 0x90, v140
	v_cvt_pk_bf16_f32 v54, v48, v49
	v_lshl_add_u64 v[48:49], v[60:61], 0, v[128:129]
	v_ashrrev_i32_e32 v51, 31, v50
	global_store_dwordx4 v[48:49], v[52:55], off
	v_lshl_add_u64 v[48:49], v[50:51], 4, s[36:37]
	s_nop 1
	v_mov_b64_e32 v[52:53], v[240:241]
	v_mov_b64_e32 v[54:55], v[242:243]
	s_and_b64 vcc, exec, s[10:11]
	s_mov_b64 s[20:21], -1
	s_waitcnt vmcnt(0)
	v_add_f32_e32 v48, v52, v53
	v_add_f32_e32 v49, v54, v55
	v_add_f32_e32 v49, v48, v49
	s_cbranch_vccnz .LBB0_513
	v_fmamk_f32 v48, v49, 0x3c000000, v252
	v_mul_f32_e32 v52, 0x4b800000, v48
	v_cmp_gt_f32_e32 vcc, s49, v48
	s_mov_b64 s[20:21], 0
	s_nop 0
	v_cndmask_b32_e32 v48, v48, v52, vcc
	v_rsq_f32_e32 v48, v48
	s_nop 0
	v_mul_f32_e32 v52, 0x45800000, v48
	v_cndmask_b32_e32 v48, v48, v52, vcc

; __device__ __forceinline__ unsigned cvt_pk_bf16(float lo, float hi) { const f32x2 v = {lo, hi}; return __builtin_bit_cast(unsigned, __builtin_convertvector(v, bf16x2_t)); }
; __device__ __forceinline__ float sum4(f32x4 v) { return (v.x + v.y) + (v.z + v.w); }
;     template <int A0, int A1> __device__ __forceinline__ void run(const f32x4 (&acc)[2][2][4][2], const Unit& u, int wr, int wc, int fr, int fq) const {
;     ...
;             for (int m = 0; m < 4; ++m) {
;                 const int row = row0 + ai * 128 + m * 16;
;                 const f32x4 pv = isq ? *(const f32x4*)(ssqq + (size_t)row * 4) : *(const f32x4*)(ssqkv + (size_t)row * 4);
;                 const float rr = isq ? rsqrtf(sum4(pv) * (1.0f / 256.0f) + EPS) * C2 : rsqrtf(sum4(pv) * (1.0f / 128.0f) + EPS);
; #pragma unroll
;                 for (int bj = 0; bj < 2; ++bj) {
;                     const int cbase = lpn * 256 + bj * 128 + wc * 32;
;                     f32x4 v0 = acc[ai][bj][m][0] * rr, v1 = acc[ai][bj][m][1] * rr;
;                     if (isq && ((cbase >> 5) % 3) == 2 && u.pm < 64) rope_apply(v0, v1, rope, row, fq);
;                     u32x4 w; w.x = cvt_pk_bf16(v0.x, v0.y); w.y = cvt_pk_bf16(v0.z, v0.w); w.z = cvt_pk_bf16(v1.x, v1.y); w.w = cvt_pk_bf16(v1.z, v1.w);
;                     if (isq) *(u32x4*)(Q + (size_t)row * 768 + cbase + fq * 8) = w;
.LBB0_529:
	v_cvt_pk_bf16_f32 v36, v36, v37
	v_cvt_pk_bf16_f32 v37, v38, v39
	v_cvt_pk_bf16_f32 v39, v34, v35
	v_add_u32_e32 v34, 0xa0, v140
	v_cvt_pk_bf16_f32 v38, v32, v33
	v_lshl_add_u64 v[32:33], v[44:45], 0, v[128:129]
	v_ashrrev_i32_e32 v35, 31, v34
	global_store_dwordx4 v[32:33], v[36:39], off
	v_lshl_add_u64 v[32:33], v[34:35], 4, s[36:37]
	s_nop 1
	v_mov_b64_e32 v[36:37], v[244:245]
	v_mov_b64_e32 v[38:39], v[246:247]
	s_and_b64 vcc, exec, s[10:11]
	s_mov_b64 s[20:21], -1
	s_waitcnt vmcnt(0)
	v_add_f32_e32 v32, v36, v37
	v_add_f32_e32 v33, v38, v39
	v_add_f32_e32 v33, v32, v33
	s_cbranch_vccnz .LBB0_531
	v_fmamk_f32 v32, v33, 0x3c000000, v252
	v_mul_f32_e32 v36, 0x4b800000, v32
	v_cmp_gt_f32_e32 vcc, s49, v32
	s_mov_b64 s[20:21], 0
	s_nop 0
	v_cndmask_b32_e32 v32, v32, v36, vcc
	v_rsq_f32_e32 v32, v32
	s_nop 0
	v_mul_f32_e32 v36, 0x45800000, v32
	v_cndmask_b32_e32 v32, v32, v36, vcc

; __device__ __forceinline__ unsigned cvt_pk_bf16(float lo, float hi) { const f32x2 v = {lo, hi}; return __builtin_bit_cast(unsigned, __builtin_convertvector(v, bf16x2_t)); }
; __device__ __forceinline__ float sum4(f32x4 v) { return (v.x + v.y) + (v.z + v.w); }
;     template <int A0, int A1> __device__ __forceinline__ void run(const f32x4 (&acc)[2][2][4][2], const Unit& u, int wr, int wc, int fr, int fq) const {
;     ...
;             for (int m = 0; m < 4; ++m) {
;                 const int row = row0 + ai * 128 + m * 16;
;                 const f32x4 pv = isq ? *(const f32x4*)(ssqq + (size_t)row * 4) : *(const f32x4*)(ssqkv + (size_t)row * 4);
;                 const float rr = isq ? rsqrtf(sum4(pv) * (1.0f / 256.0f) + EPS) * C2 : rsqrtf(sum4(pv) * (1.0f / 128.0f) + EPS);
; #pragma unroll
;                 for (int bj = 0; bj < 2; ++bj) {
;                     const int cbase = lpn * 256 + bj * 128 + wc * 32;
;                     f32x4 v0 = acc[ai][bj][m][0] * rr, v1 = acc[ai][bj][m][1] * rr;
;                     if (isq && ((cbase >> 5) % 3) == 2 && u.pm < 64) rope_apply(v0, v1, rope, row, fq);
;                     u32x4 w; w.x = cvt_pk_bf16(v0.x, v0.y); w.y = cvt_pk_bf16(v0.z, v0.w); w.z = cvt_pk_bf16(v1.x, v1.y); w.w = cvt_pk_bf16(v1.z, v1.w);
;                     if (isq) *(u32x4*)(Q + (size_t)row * 768 + cbase + fq * 8) = w;
.LBB0_547:
	v_cvt_pk_bf16_f32 v20, v20, v21
	v_cvt_pk_bf16_f32 v21, v22, v23
	v_cvt_pk_bf16_f32 v23, v18, v19
	v_add_u32_e32 v18, 0xb0, v140
	v_cvt_pk_bf16_f32 v22, v16, v17
	v_lshl_add_u64 v[16:17], v[28:29], 0, v[128:129]
	v_ashrrev_i32_e32 v19, 31, v18
	global_store_dwordx4 v[16:17], v[20:23], off
	v_lshl_add_u64 v[16:17], v[18:19], 4, s[36:37]
	s_nop 1
	v_mov_b64_e32 v[20:21], v[248:249]
	v_mov_b64_e32 v[22:23], v[250:251]
	s_and_b64 vcc, exec, s[10:11]
	s_mov_b64 s[20:21], -1
	s_waitcnt vmcnt(0)
	v_add_f32_e32 v16, v20, v21
	v_add_f32_e32 v17, v22, v23
	v_add_f32_e32 v17, v16, v17
	s_cbranch_vccnz .LBB0_549
	v_fmamk_f32 v16, v17, 0x3c000000, v252
	v_mul_f32_e32 v20, 0x4b800000, v16
	v_cmp_gt_f32_e32 vcc, s49, v16
	s_mov_b64 s[20:21], 0
	s_nop 0
	v_cndmask_b32_e32 v16, v16, v20, vcc
	v_rsq_f32_e32 v16, v16
	s_nop 0
	v_mul_f32_e32 v20, 0x45800000, v16
	v_cndmask_b32_e32 v16, v16, v20, vcc

; __device__ __forceinline__ float sum4(f32x4 v) { return (v.x + v.y) + (v.z + v.w); }
;     template <int A0, int A1> __device__ __forceinline__ void run(const f32x4 (&acc)[2][2][4][2], const Unit& u, int wr, int wc, int fr, int fq) const {
;         const int lpn = u.pn + pn_off;
;         const bool isq = lpn < 3;
;         const int row0 = u.pm * 256 + wr * 64 + fr;
; #pragma unroll
;         for (int ai = A0; ai < A1; ++ai)
; #pragma unroll
;             for (int m = 0; m < 4; ++m) {
;                 const int row = row0 + ai * 128 + m * 16;
;                 const f32x4 pv = isq ? *(const f32x4*)(ssqq + (size_t)row * 4) : *(const f32x4*)(ssqkv + (size_t)row * 4);
;                 const float rr = isq ? rsqrtf(sum4(pv) * (1.0f / 256.0f) + EPS) * C2 : rsqrtf(sum4(pv) * (1.0f / 128.0f) + EPS);
.LBB0_591:
	s_cmp_gt_i32 s20, -1
	s_cselect_b64 s[46:47], -1, 0
	s_lshl_b32 s14, s86, 8
	s_add_i32 s14, s14, s52
	s_cmp_lt_i32 s20, 0
	s_cselect_b64 s[10:11], -1, 0
	v_or_b32_e32 v140, s14, v139
	s_and_b64 s[8:9], s[10:11], exec
	v_ashrrev_i32_e32 v141, 31, v140
	s_cselect_b32 s39, s44, s83
	s_cselect_b32 s38, s75, s82
	v_lshl_add_u64 v[142:143], v[140:141], 4, s[38:39]
	global_load_dwordx4 v[204:207], v[142:143], off offset:256
	global_load_dwordx4 v[208:211], v[142:143], off offset:512
	global_load_dwordx4 v[212:215], v[142:143], off offset:768
	global_load_dwordx4 v[220:223], v[142:143], off offset:2048
	global_load_dwordx4 v[224:227], v[142:143], off offset:2304
	global_load_dwordx4 v[228:231], v[142:143], off offset:2560
	global_load_dwordx4 v[232:235], v[142:143], off offset:2816
	global_load_dwordx4 v[144:147], v[142:143], off
	s_mov_b64 s[8:9], -1
	s_and_b64 vcc, exec, s[46:47]
	s_waitcnt vmcnt(0)
	v_add_f32_e32 v128, v144, v145
	v_add_f32_e32 v143, v146, v147
	v_add_f32_e32 v128, v128, v143
	s_cbranch_vccz .LBB0_593
	v_fmamk_f32 v142, v128, 0x3c000000, v252
	v_mul_f32_e32 v143, 0x4b800000, v142
	v_cmp_gt_f32_e32 vcc, s49, v142
	s_mov_b64 s[8:9], 0
	s_nop 0
	v_cndmask_b32_e32 v142, v142, v143, vcc
	v_rsq_f32_e32 v142, v142
	s_nop 0
	v_mul_f32_e32 v143, 0x45800000, v142
	v_cndmask_b32_e32 v142, v142, v143, vcc

; __device__ __forceinline__ unsigned cvt_pk_bf16(float lo, float hi) { const f32x2 v = {lo, hi}; return __builtin_bit_cast(unsigned, __builtin_convertvector(v, bf16x2_t)); }
; __device__ __forceinline__ float sum4(f32x4 v) { return (v.x + v.y) + (v.z + v.w); }
;     template <int A0, int A1> __device__ __forceinline__ void run(const f32x4 (&acc)[2][2][4][2], const Unit& u, int wr, int wc, int fr, int fq) const {
;     ...
;             for (int m = 0; m < 4; ++m) {
;                 const int row = row0 + ai * 128 + m * 16;
;                 const f32x4 pv = isq ? *(const f32x4*)(ssqq + (size_t)row * 4) : *(const f32x4*)(ssqkv + (size_t)row * 4);
;                 const float rr = isq ? rsqrtf(sum4(pv) * (1.0f / 256.0f) + EPS) * C2 : rsqrtf(sum4(pv) * (1.0f / 128.0f) + EPS);
; #pragma unroll
;                 for (int bj = 0; bj < 2; ++bj) {
;                     const int cbase = lpn * 256 + bj * 128 + wc * 32;
;                     f32x4 v0 = acc[ai][bj][m][0] * rr, v1 = acc[ai][bj][m][1] * rr;
;                     if (isq && ((cbase >> 5) % 3) == 2 && u.pm < 64) rope_apply(v0, v1, rope, row, fq);
;                     u32x4 w; w.x = cvt_pk_bf16(v0.x, v0.y); w.y = cvt_pk_bf16(v0.z, v0.w); w.z = cvt_pk_bf16(v1.x, v1.y); w.w = cvt_pk_bf16(v1.z, v1.w);
;                     if (isq) *(u32x4*)(Q + (size_t)row * 768 + cbase + fq * 8) = w;
.LBB0_609:
	v_cvt_pk_bf16_f32 v116, v116, v117
	v_cvt_pk_bf16_f32 v117, v118, v119
	v_cvt_pk_bf16_f32 v119, v114, v115
	v_or_b32_e32 v114, 16, v140
	v_cvt_pk_bf16_f32 v118, v112, v113
	v_lshl_add_u64 v[112:113], v[124:125], 0, v[128:129]
	v_ashrrev_i32_e32 v115, 31, v114
	global_store_dwordx4 v[112:113], v[116:119], off
	v_lshl_add_u64 v[112:113], v[114:115], 4, s[38:39]
	s_nop 1
	v_mov_b64_e32 v[116:117], v[204:205]
	v_mov_b64_e32 v[118:119], v[206:207]
	s_and_b64 vcc, exec, s[10:11]
	s_mov_b64 s[20:21], -1
	s_waitcnt vmcnt(0)
	v_add_f32_e32 v112, v116, v117
	v_add_f32_e32 v113, v118, v119
	v_add_f32_e32 v113, v112, v113
	s_cbranch_vccnz .LBB0_611
	v_fmamk_f32 v112, v113, 0x3c000000, v252
	v_mul_f32_e32 v116, 0x4b800000, v112
	v_cmp_gt_f32_e32 vcc, s49, v112
	s_mov_b64 s[20:21], 0
	s_nop 0
	v_cndmask_b32_e32 v112, v112, v116, vcc
	v_rsq_f32_e32 v112, v112
	s_nop 0
	v_mul_f32_e32 v116, 0x45800000, v112
	v_cndmask_b32_e32 v112, v112, v116, vcc

; __device__ __forceinline__ unsigned cvt_pk_bf16(float lo, float hi) { const f32x2 v = {lo, hi}; return __builtin_bit_cast(unsigned, __builtin_convertvector(v, bf16x2_t)); }
; __device__ __forceinline__ float sum4(f32x4 v) { return (v.x + v.y) + (v.z + v.w); }
;     template <int A0, int A1> __device__ __forceinline__ void run(const f32x4 (&acc)[2][2][4][2], const Unit& u, int wr, int wc, int fr, int fq) const {
;     ...
;             for (int m = 0; m < 4; ++m) {
;                 const int row = row0 + ai * 128 + m * 16;
;                 const f32x4 pv = isq ? *(const f32x4*)(ssqq + (size_t)row * 4) : *(const f32x4*)(ssqkv + (size_t)row * 4);
;                 const float rr = isq ? rsqrtf(sum4(pv) * (1.0f / 256.0f) + EPS) * C2 : rsqrtf(sum4(pv) * (1.0f / 128.0f) + EPS);
; #pragma unroll
;                 for (int bj = 0; bj < 2; ++bj) {
;                     const int cbase = lpn * 256 + bj * 128 + wc * 32;
;                     f32x4 v0 = acc[ai][bj][m][0] * rr, v1 = acc[ai][bj][m][1] * rr;
;                     if (isq && ((cbase >> 5) % 3) == 2 && u.pm < 64) rope_apply(v0, v1, rope, row, fq);
;                     u32x4 w; w.x = cvt_pk_bf16(v0.x, v0.y); w.y = cvt_pk_bf16(v0.z, v0.w); w.z = cvt_pk_bf16(v1.x, v1.y); w.w = cvt_pk_bf16(v1.z, v1.w);
;                     if (isq) *(u32x4*)(Q + (size_t)row * 768 + cbase + fq * 8) = w;
.LBB0_627:
	v_cvt_pk_bf16_f32 v100, v100, v101
	v_cvt_pk_bf16_f32 v101, v102, v103
	v_cvt_pk_bf16_f32 v103, v98, v99
	v_or_b32_e32 v98, 32, v140
	v_cvt_pk_bf16_f32 v102, v96, v97
	v_lshl_add_u64 v[96:97], v[108:109], 0, v[128:129]
	v_ashrrev_i32_e32 v99, 31, v98
	global_store_dwordx4 v[96:97], v[100:103], off
	v_lshl_add_u64 v[96:97], v[98:99], 4, s[38:39]
	s_nop 1
	v_mov_b64_e32 v[100:101], v[208:209]
	v_mov_b64_e32 v[102:103], v[210:211]
	s_and_b64 vcc, exec, s[10:11]
	s_mov_b64 s[20:21], -1
	s_waitcnt vmcnt(0)
	v_add_f32_e32 v96, v100, v101
	v_add_f32_e32 v97, v102, v103
	v_add_f32_e32 v97, v96, v97
	s_cbranch_vccnz .LBB0_629
	v_fmamk_f32 v96, v97, 0x3c000000, v252
	v_mul_f32_e32 v100, 0x4b800000, v96
	v_cmp_gt_f32_e32 vcc, s49, v96
	s_mov_b64 s[20:21], 0
	s_nop 0
	v_cndmask_b32_e32 v96, v96, v100, vcc
	v_rsq_f32_e32 v96, v96
	s_nop 0
	v_mul_f32_e32 v100, 0x45800000, v96
	v_cndmask_b32_e32 v96, v96, v100, vcc

; __device__ __forceinline__ unsigned cvt_pk_bf16(float lo, float hi) { const f32x2 v = {lo, hi}; return __builtin_bit_cast(unsigned, __builtin_convertvector(v, bf16x2_t)); }
; __device__ __forceinline__ float sum4(f32x4 v) { return (v.x + v.y) + (v.z + v.w); }
;     template <int A0, int A1> __device__ __forceinline__ void run(const f32x4 (&acc)[2][2][4][2], const Unit& u, int wr, int wc, int fr, int fq) const {
;     ...
;             for (int m = 0; m < 4; ++m) {
;                 const int row = row0 + ai * 128 + m * 16;
;                 const f32x4 pv = isq ? *(const f32x4*)(ssqq + (size_t)row * 4) : *(const f32x4*)(ssqkv + (size_t)row * 4);
;                 const float rr = isq ? rsqrtf(sum4(pv) * (1.0f / 256.0f) + EPS) * C2 : rsqrtf(sum4(pv) * (1.0f / 128.0f) + EPS);
; #pragma unroll
;                 for (int bj = 0; bj < 2; ++bj) {
;                     const int cbase = lpn * 256 + bj * 128 + wc * 32;
;                     f32x4 v0 = acc[ai][bj][m][0] * rr, v1 = acc[ai][bj][m][1] * rr;
;                     if (isq && ((cbase >> 5) % 3) == 2 && u.pm < 64) rope_apply(v0, v1, rope, row, fq);
;                     u32x4 w; w.x = cvt_pk_bf16(v0.x, v0.y); w.y = cvt_pk_bf16(v0.z, v0.w); w.z = cvt_pk_bf16(v1.x, v1.y); w.w = cvt_pk_bf16(v1.z, v1.w);
;                     if (isq) *(u32x4*)(Q + (size_t)row * 768 + cbase + fq * 8) = w;
.LBB0_645:
	v_cvt_pk_bf16_f32 v84, v84, v85
	v_cvt_pk_bf16_f32 v85, v86, v87
	v_cvt_pk_bf16_f32 v87, v82, v83
	v_or_b32_e32 v82, 48, v140
	v_cvt_pk_bf16_f32 v86, v80, v81
	v_lshl_add_u64 v[80:81], v[92:93], 0, v[128:129]
	v_ashrrev_i32_e32 v83, 31, v82
	global_store_dwordx4 v[80:81], v[84:87], off
	v_lshl_add_u64 v[80:81], v[82:83], 4, s[38:39]
	s_nop 1
	v_mov_b64_e32 v[84:85], v[212:213]
	v_mov_b64_e32 v[86:87], v[214:215]
	s_and_b64 vcc, exec, s[10:11]
	s_mov_b64 s[20:21], -1
	s_waitcnt vmcnt(0)
	v_add_f32_e32 v80, v84, v85
	v_add_f32_e32 v81, v86, v87
	v_add_f32_e32 v81, v80, v81
	s_cbranch_vccnz .LBB0_647
	v_fmamk_f32 v80, v81, 0x3c000000, v252
	v_mul_f32_e32 v84, 0x4b800000, v80
	v_cmp_gt_f32_e32 vcc, s49, v80
	s_mov_b64 s[20:21], 0
	s_nop 0
	v_cndmask_b32_e32 v80, v80, v84, vcc
	v_rsq_f32_e32 v80, v80
	s_nop 0
	v_mul_f32_e32 v84, 0x45800000, v80
	v_cndmask_b32_e32 v80, v80, v84, vcc

; __device__ __forceinline__ unsigned cvt_pk_bf16(float lo, float hi) { const f32x2 v = {lo, hi}; return __builtin_bit_cast(unsigned, __builtin_convertvector(v, bf16x2_t)); }
; __device__ __forceinline__ float sum4(f32x4 v) { return (v.x + v.y) + (v.z + v.w); }
;     template <int A0, int A1> __device__ __forceinline__ void run(const f32x4 (&acc)[2][2][4][2], const Unit& u, int wr, int wc, int fr, int fq) const {
;     ...
;             for (int m = 0; m < 4; ++m) {
;                 const int row = row0 + ai * 128 + m * 16;
;                 const f32x4 pv = isq ? *(const f32x4*)(ssqq + (size_t)row * 4) : *(const f32x4*)(ssqkv + (size_t)row * 4);
;                 const float rr = isq ? rsqrtf(sum4(pv) * (1.0f / 256.0f) + EPS) * C2 : rsqrtf(sum4(pv) * (1.0f / 128.0f) + EPS);
; #pragma unroll
;                 for (int bj = 0; bj < 2; ++bj) {
;                     const int cbase = lpn * 256 + bj * 128 + wc * 32;
;                     f32x4 v0 = acc[ai][bj][m][0] * rr, v1 = acc[ai][bj][m][1] * rr;
;                     if (isq && ((cbase >> 5) % 3) == 2 && u.pm < 64) rope_apply(v0, v1, rope, row, fq);
;                     u32x4 w; w.x = cvt_pk_bf16(v0.x, v0.y); w.y = cvt_pk_bf16(v0.z, v0.w); w.z = cvt_pk_bf16(v1.x, v1.y); w.w = cvt_pk_bf16(v1.z, v1.w);
;                     if (isq) *(u32x4*)(Q + (size_t)row * 768 + cbase + fq * 8) = w;
.LBB0_663:
	v_cvt_pk_bf16_f32 v68, v68, v69
	v_cvt_pk_bf16_f32 v69, v70, v71
	v_cvt_pk_bf16_f32 v71, v66, v67
	v_add_u32_e32 v66, 0x80, v140
	v_cvt_pk_bf16_f32 v70, v64, v65
	v_lshl_add_u64 v[64:65], v[76:77], 0, v[128:129]
	v_ashrrev_i32_e32 v67, 31, v66
	global_store_dwordx4 v[64:65], v[68:71], off
	v_lshl_add_u64 v[64:65], v[66:67], 4, s[38:39]
	s_nop 1
	v_mov_b64_e32 v[68:69], v[220:221]
	v_mov_b64_e32 v[70:71], v[222:223]
	s_and_b64 vcc, exec, s[10:11]
	s_mov_b64 s[20:21], -1
	s_waitcnt vmcnt(0)
	v_add_f32_e32 v64, v68, v69
	v_add_f32_e32 v65, v70, v71
	v_add_f32_e32 v65, v64, v65
	s_cbranch_vccnz .LBB0_665
	v_fmamk_f32 v64, v65, 0x3c000000, v252
	v_mul_f32_e32 v68, 0x4b800000, v64
	v_cmp_gt_f32_e32 vcc, s49, v64
	s_mov_b64 s[20:21], 0
	s_nop 0
	v_cndmask_b32_e32 v64, v64, v68, vcc
	v_rsq_f32_e32 v64, v64
	s_nop 0
	v_mul_f32_e32 v68, 0x45800000, v64
	v_cndmask_b32_e32 v64, v64, v68, vcc

; __device__ __forceinline__ unsigned cvt_pk_bf16(float lo, float hi) { const f32x2 v = {lo, hi}; return __builtin_bit_cast(unsigned, __builtin_convertvector(v, bf16x2_t)); }
; __device__ __forceinline__ float sum4(f32x4 v) { return (v.x + v.y) + (v.z + v.w); }
;     template <int A0, int A1> __device__ __forceinline__ void run(const f32x4 (&acc)[2][2][4][2], const Unit& u, int wr, int wc, int fr, int fq) const {
;     ...
;             for (int m = 0; m < 4; ++m) {
;                 const int row = row0 + ai * 128 + m * 16;
;                 const f32x4 pv = isq ? *(const f32x4*)(ssqq + (size_t)row * 4) : *(const f32x4*)(ssqkv + (size_t)row * 4);
;                 const float rr = isq ? rsqrtf(sum4(pv) * (1.0f / 256.0f) + EPS) * C2 : rsqrtf(sum4(pv) * (1.0f / 128.0f) + EPS);
; #pragma unroll
;                 for (int bj = 0; bj < 2; ++bj) {
;                     const int cbase = lpn * 256 + bj * 128 + wc * 32;
;                     f32x4 v0 = acc[ai][bj][m][0] * rr, v1 = acc[ai][bj][m][1] * rr;
;                     if (isq && ((cbase >> 5) % 3) == 2 && u.pm < 64) rope_apply(v0, v1, rope, row, fq);
;                     u32x4 w; w.x = cvt_pk_bf16(v0.x, v0.y); w.y = cvt_pk_bf16(v0.z, v0.w); w.z = cvt_pk_bf16(v1.x, v1.y); w.w = cvt_pk_bf16(v1.z, v1.w);
;                     if (isq) *(u32x4*)(Q + (size_t)row * 768 + cbase + fq * 8) = w;
.LBB0_681:
	v_cvt_pk_bf16_f32 v52, v52, v53
	v_cvt_pk_bf16_f32 v53, v54, v55
	v_cvt_pk_bf16_f32 v55, v50, v51
	v_add_u32_e32 v50, 0x90, v140
	v_cvt_pk_bf16_f32 v54, v48, v49
	v_lshl_add_u64 v[48:49], v[60:61], 0, v[128:129]
	v_ashrrev_i32_e32 v51, 31, v50
	global_store_dwordx4 v[48:49], v[52:55], off
	v_lshl_add_u64 v[48:49], v[50:51], 4, s[38:39]
	s_nop 1
	v_mov_b64_e32 v[52:53], v[224:225]
	v_mov_b64_e32 v[54:55], v[226:227]
	s_and_b64 vcc, exec, s[10:11]
	s_mov_b64 s[20:21], -1
	s_waitcnt vmcnt(0)
	v_add_f32_e32 v48, v52, v53
	v_add_f32_e32 v49, v54, v55
	v_add_f32_e32 v49, v48, v49
	s_cbranch_vccnz .LBB0_683
	v_fmamk_f32 v48, v49, 0x3c000000, v252
	v_mul_f32_e32 v52, 0x4b800000, v48
	v_cmp_gt_f32_e32 vcc, s49, v48
	s_mov_b64 s[20:21], 0
	s_nop 0
	v_cndmask_b32_e32 v48, v48, v52, vcc
	v_rsq_f32_e32 v48, v48
	s_nop 0
	v_mul_f32_e32 v52, 0x45800000, v48
	v_cndmask_b32_e32 v48, v48, v52, vcc

; __device__ __forceinline__ unsigned cvt_pk_bf16(float lo, float hi) { const f32x2 v = {lo, hi}; return __builtin_bit_cast(unsigned, __builtin_convertvector(v, bf16x2_t)); }
; __device__ __forceinline__ float sum4(f32x4 v) { return (v.x + v.y) + (v.z + v.w); }
;     template <int A0, int A1> __device__ __forceinline__ void run(const f32x4 (&acc)[2][2][4][2], const Unit& u, int wr, int wc, int fr, int fq) const {
;     ...
;             for (int m = 0; m < 4; ++m) {
;                 const int row = row0 + ai * 128 + m * 16;
;                 const f32x4 pv = isq ? *(const f32x4*)(ssqq + (size_t)row * 4) : *(const f32x4*)(ssqkv + (size_t)row * 4);
;                 const float rr = isq ? rsqrtf(sum4(pv) * (1.0f / 256.0f) + EPS) * C2 : rsqrtf(sum4(pv) * (1.0f / 128.0f) + EPS);
; #pragma unroll
;                 for (int bj = 0; bj < 2; ++bj) {
;                     const int cbase = lpn * 256 + bj * 128 + wc * 32;
;                     f32x4 v0 = acc[ai][bj][m][0] * rr, v1 = acc[ai][bj][m][1] * rr;
;                     if (isq && ((cbase >> 5) % 3) == 2 && u.pm < 64) rope_apply(v0, v1, rope, row, fq);
;                     u32x4 w; w.x = cvt_pk_bf16(v0.x, v0.y); w.y = cvt_pk_bf16(v0.z, v0.w); w.z = cvt_pk_bf16(v1.x, v1.y); w.w = cvt_pk_bf16(v1.z, v1.w);
;                     if (isq) *(u32x4*)(Q + (size_t)row * 768 + cbase + fq * 8) = w;
.LBB0_699:
	v_cvt_pk_bf16_f32 v36, v36, v37
	v_cvt_pk_bf16_f32 v37, v38, v39
	v_cvt_pk_bf16_f32 v39, v34, v35
	v_add_u32_e32 v34, 0xa0, v140
	v_cvt_pk_bf16_f32 v38, v32, v33
	v_lshl_add_u64 v[32:33], v[44:45], 0, v[128:129]
	v_ashrrev_i32_e32 v35, 31, v34
	global_store_dwordx4 v[32:33], v[36:39], off
	v_lshl_add_u64 v[32:33], v[34:35], 4, s[38:39]
	s_nop 1
	v_mov_b64_e32 v[36:37], v[228:229]
	v_mov_b64_e32 v[38:39], v[230:231]
	s_and_b64 vcc, exec, s[10:11]
	s_mov_b64 s[20:21], -1
	s_waitcnt vmcnt(0)
	v_add_f32_e32 v32, v36, v37
	v_add_f32_e32 v33, v38, v39
	v_add_f32_e32 v33, v32, v33
	s_cbranch_vccnz .LBB0_701
	v_fmamk_f32 v32, v33, 0x3c000000, v252
	v_mul_f32_e32 v36, 0x4b800000, v32
	v_cmp_gt_f32_e32 vcc, s49, v32
	s_mov_b64 s[20:21], 0
	s_nop 0
	v_cndmask_b32_e32 v32, v32, v36, vcc
	v_rsq_f32_e32 v32, v32
	s_nop 0
	v_mul_f32_e32 v36, 0x45800000, v32
	v_cndmask_b32_e32 v32, v32, v36, vcc

; __device__ __forceinline__ unsigned cvt_pk_bf16(float lo, float hi) { const f32x2 v = {lo, hi}; return __builtin_bit_cast(unsigned, __builtin_convertvector(v, bf16x2_t)); }
; __device__ __forceinline__ float sum4(f32x4 v) { return (v.x + v.y) + (v.z + v.w); }
;     template <int A0, int A1> __device__ __forceinline__ void run(const f32x4 (&acc)[2][2][4][2], const Unit& u, int wr, int wc, int fr, int fq) const {
;     ...
;             for (int m = 0; m < 4; ++m) {
;                 const int row = row0 + ai * 128 + m * 16;
;                 const f32x4 pv = isq ? *(const f32x4*)(ssqq + (size_t)row * 4) : *(const f32x4*)(ssqkv + (size_t)row * 4);
;                 const float rr = isq ? rsqrtf(sum4(pv) * (1.0f / 256.0f) + EPS) * C2 : rsqrtf(sum4(pv) * (1.0f / 128.0f) + EPS);
; #pragma unroll
;                 for (int bj = 0; bj < 2; ++bj) {
;                     const int cbase = lpn * 256 + bj * 128 + wc * 32;
;                     f32x4 v0 = acc[ai][bj][m][0] * rr, v1 = acc[ai][bj][m][1] * rr;
;                     if (isq && ((cbase >> 5) % 3) == 2 && u.pm < 64) rope_apply(v0, v1, rope, row, fq);
;                     u32x4 w; w.x = cvt_pk_bf16(v0.x, v0.y); w.y = cvt_pk_bf16(v0.z, v0.w); w.z = cvt_pk_bf16(v1.x, v1.y); w.w = cvt_pk_bf16(v1.z, v1.w);
;                     if (isq) *(u32x4*)(Q + (size_t)row * 768 + cbase + fq * 8) = w;
.LBB0_717:
	v_cvt_pk_bf16_f32 v20, v20, v21
	v_cvt_pk_bf16_f32 v21, v22, v23
	v_cvt_pk_bf16_f32 v23, v18, v19
	v_add_u32_e32 v18, 0xb0, v140
	v_cvt_pk_bf16_f32 v22, v16, v17
	v_lshl_add_u64 v[16:17], v[28:29], 0, v[128:129]
	v_ashrrev_i32_e32 v19, 31, v18
	global_store_dwordx4 v[16:17], v[20:23], off
	v_lshl_add_u64 v[16:17], v[18:19], 4, s[38:39]
	s_nop 1
	v_mov_b64_e32 v[20:21], v[232:233]
	v_mov_b64_e32 v[22:23], v[234:235]
	s_and_b64 vcc, exec, s[10:11]
	s_mov_b64 s[20:21], -1
	s_waitcnt vmcnt(0)
	v_add_f32_e32 v16, v20, v21
	v_add_f32_e32 v17, v22, v23
	v_add_f32_e32 v17, v16, v17
	s_cbranch_vccnz .LBB0_719
	v_fmamk_f32 v16, v17, 0x3c000000, v252
	v_mul_f32_e32 v20, 0x4b800000, v16
	v_cmp_gt_f32_e32 vcc, s49, v16
	s_mov_b64 s[20:21], 0
	s_nop 0
	v_cndmask_b32_e32 v16, v16, v20, vcc
	v_rsq_f32_e32 v16, v16
	s_nop 0
	v_mul_f32_e32 v20, 0x45800000, v16
	v_cndmask_b32_e32 v16, v16, v20, vcc

; #define LAS __attribute__((address_space(3)))
; __device__ __forceinline__ float sum4(f32x4 v) { return (v.x + v.y) + (v.z + v.w); }
; __device__ __forceinline__ float dot4(f32x4 v) { return (v.x * v.x + v.y * v.y) + (v.z * v.z + v.w * v.w); }
; __device__ __forceinline__ float quad_sum(float t, int lane) { t += shx(t, 16, lane); t += shx(t, 32, lane); return t; }
;     template <int A0, int A1> __device__ __forceinline__ void run(const f32x4 (&acc)[2][2][4][2], const Unit& u, int wr, int wc, int fr, int fq) const {
;     ...
;         const int row0 = u.pm * 256 + wr * 64 + fr;
; #pragma unroll
;         for (int ai = A0; ai < A1; ++ai)
; #pragma unroll
;             for (int m = 0; m < 4; ++m) {
;                 const int row = row0 + ai * 128 + m * 16;
;                 const float t = quad_sum(sum4(*(const f32x4*)(ssqp + (size_t)row * 16 + 4 * fq)), fq * 16 + fr);
;                 const float rr = rsqrtf(t * (1.0f / 1024.0f) + EPS);
;                 f32x4 v[2][2];
; #pragma unroll
;                 for (int bj = 0; bj < 2; ++bj)
; #pragma unroll
;                     for (int n = 0; n < 2; ++n) v[bj][n] = acc[ai][bj][m][n] * rr + b[bj][n];
;                 if (u.pn == 0) {
;                     const float q = quad_sum((dot4(v[0][0]) + dot4(v[0][1])) + (dot4(v[1][0]) + dot4(v[1][1])), fq * 16 + fr);
;                     if (fq == 0) ssqq[(size_t)row * 4 + wc] = q;
;                 } else if (u.pn == 1) {
;                     const float q = quad_sum(dot4(v[0][0]) + dot4(v[0][1]), fq * 16 + fr);
;                     if (fq == 0) ssqkv[(size_t)row * 4 + wc] = q;
; template <class Epi, int AI>
; __device__ __forceinline__ void skinny_item(LAS unsigned char* lds, const Gemm g, const Epi& E, const Unit u, int wr, int wc, int wave, int lane) {
;     ...
; #pragma unroll 1
;         for (int w = 0; w < 7; ++w) {
; #pragma unroll
;             for (int bj = 0; bj < 2; ++bj)
; #pragma unroll
;                 for (int m = 0; m < 4; ++m)
; #pragma unroll
;                     for (int n = 0; n < 2; ++n) acc[AI][bj][m][n] += *(const LAS f32x4*)(lds + ((w * 16 + bj * 8 + m * 2 + n) * 64 + lane) * 16);
;         }
.LBB0_933:
	v_add_u32_e32 v56, s6, v81
	ds_read_b128 v[190:193], v56
	ds_read_b128 v[194:197], v56 offset:1024
	ds_read_b128 v[198:201], v56 offset:2048
	ds_read_b128 v[202:205], v56 offset:3072
	ds_read_b128 v[206:209], v56 offset:4096
	ds_read_b128 v[210:213], v56 offset:5120
	ds_read_b128 v[214:217], v56 offset:6144
	ds_read_b128 v[218:221], v56 offset:7168
	ds_read_b128 v[222:225], v56 offset:8192
	ds_read_b128 v[226:229], v56 offset:9216
	ds_read_b128 v[230:233], v56 offset:10240
	ds_read_b128 v[234:237], v56 offset:11264
	ds_read_b128 v[240:243], v56 offset:12288
	ds_read_b128 v[244:247], v56 offset:13312
	ds_read_b128 v[248:251], v56 offset:14336
	ds_read_b128 v[48:51], v56 offset:15360
	s_waitcnt lgkmcnt(0)
	v_pk_add_f32 v[66:67], v[66:67], v[192:193]
	v_pk_add_f32 v[64:65], v[64:65], v[190:191]
	v_pk_add_f32 v[70:71], v[70:71], v[196:197]
	v_pk_add_f32 v[68:69], v[68:69], v[194:195]
	v_pk_add_f32 v[46:47], v[46:47], v[200:201]
	v_pk_add_f32 v[44:45], v[44:45], v[198:199]
	v_pk_add_f32 v[42:43], v[42:43], v[204:205]
	v_pk_add_f32 v[40:41], v[40:41], v[202:203]
	v_pk_add_f32 v[30:31], v[30:31], v[208:209]
	v_pk_add_f32 v[28:29], v[28:29], v[206:207]
	v_pk_add_f32 v[26:27], v[26:27], v[212:213]
	v_pk_add_f32 v[24:25], v[24:25], v[210:211]
	v_pk_add_f32 v[14:15], v[14:15], v[216:217]
	v_pk_add_f32 v[12:13], v[12:13], v[214:215]
	v_pk_add_f32 v[10:11], v[10:11], v[220:221]
	v_pk_add_f32 v[8:9], v[8:9], v[218:219]
	v_pk_add_f32 v[54:55], v[54:55], v[224:225]
	v_pk_add_f32 v[52:53], v[52:53], v[222:223]
	v_pk_add_f32 v[62:63], v[62:63], v[228:229]
	v_pk_add_f32 v[60:61], v[60:61], v[226:227]
	v_pk_add_f32 v[38:39], v[38:39], v[232:233]
	v_pk_add_f32 v[36:37], v[36:37], v[230:231]
	v_pk_add_f32 v[34:35], v[34:35], v[236:237]
	v_pk_add_f32 v[32:33], v[32:33], v[234:235]
	v_pk_add_f32 v[22:23], v[22:23], v[242:243]
	v_pk_add_f32 v[20:21], v[20:21], v[240:241]
	v_pk_add_f32 v[18:19], v[18:19], v[246:247]
	v_pk_add_f32 v[16:17], v[16:17], v[244:245]
	v_pk_add_f32 v[6:7], v[6:7], v[250:251]
	v_pk_add_f32 v[4:5], v[4:5], v[248:249]
	v_pk_add_f32 v[2:3], v[2:3], v[50:51]
	v_pk_add_f32 v[0:1], v[0:1], v[48:49]
	s_addk_i32 s6, 0x4000
	s_cmp_lg_u32 s6, 0x1c000
	s_cbranch_scc1 .LBB0_933
	v_lshlrev_b32_e32 v128, 6, v114
	v_lshl_add_u64 v[48:49], v[84:85], 0, v[128:129]
	global_load_dwordx4 v[48:51], v[48:49], off
	s_add_i32 s6, s26, s27
	v_add_u32_e32 v90, s6, v80
	v_ashrrev_i32_e32 v91, 31, v90
	s_cmp_lt_i32 s38, 1
	s_waitcnt vmcnt(0)
	v_mov_b32_e32 v56, v49
	v_mov_b32_e32 v57, v50
	v_mov_b32_e32 v49, v51
	v_pk_add_f32 v[48:49], v[56:57], v[48:49]
	v_lshl_add_u64 v[56:57], v[90:91], 2, s[8:9]
	v_add_f32_e32 v48, v48, v49
	ds_bpermute_b32 v49, v111, v48
	s_waitcnt lgkmcnt(0)
	v_add_f32_e32 v92, v48, v49
	global_load_dwordx4 v[76:79], v[56:57], off
	global_load_dwordx4 v[72:75], v[56:57], off offset:16
	global_load_dwordx4 v[48:51], v[56:57], off offset:528
	s_nop 0
	global_load_dwordx4 v[56:59], v[56:57], off offset:512
	ds_bpermute_b32 v115, v112, v92
	s_waitcnt lgkmcnt(0)
	v_add_f32_e32 v92, v92, v115
	v_fmamk_f32 v92, v92, 0x3a800000, v252
	v_mul_f32_e32 v115, 0x4b800000, v92
	v_cmp_gt_f32_e32 vcc, s49, v92
	s_nop 1
	v_cndmask_b32_e32 v92, v92, v115, vcc
	v_rsq_f32_e32 v92, v92
	s_nop 0
	v_mul_f32_e32 v115, 0x45800000, v92
	v_cndmask_b32_e32 v92, v92, v115, vcc
	s_waitcnt vmcnt(3)
	v_pk_fma_f32 v[64:65], v[64:65], v[92:93], v[76:77] op_sel_hi:[1,0,1]
	v_pk_fma_f32 v[66:67], v[66:67], v[92:93], v[78:79] op_sel_hi:[1,0,1]
	s_waitcnt vmcnt(2)
	v_pk_fma_f32 v[68:69], v[68:69], v[92:93], v[72:73] op_sel_hi:[1,0,1]
	v_pk_fma_f32 v[70:71], v[70:71], v[92:93], v[74:75] op_sel_hi:[1,0,1]
	s_cbranch_scc1 .LBB0_937
	s_mov_b64 s[10:11], 0
	s_cmp_eq_u32 s38, 1
	s_mov_b64 s[6:7], 0
	s_cbranch_scc0 .LBB0_938
	v_mov_b32_e32 v118, v65
	v_mov_b32_e32 v119, v69
	v_mov_b32_e32 v116, v64
	v_mov_b32_e32 v117, v68
	v_pk_mul_f32 v[118:119], v[118:119], v[118:119]
	v_mov_b32_e32 v120, v67
	v_mov_b32_e32 v121, v71
	v_pk_fma_f32 v[116:117], v[116:117], v[116:117], v[118:119]
	v_mov_b32_e32 v118, v66
	v_mov_b32_e32 v119, v70
	v_pk_mul_f32 v[120:121], v[120:121], v[120:121]
	s_and_b64 s[6:7], s[4:5], exec
	v_pk_fma_f32 v[118:119], v[118:119], v[118:119], v[120:121]
	s_nop 0
	v_pk_add_f32 v[116:117], v[116:117], v[118:119]
	s_nop 0
	v_add_f32_e32 v115, v116, v117
	ds_bpermute_b32 v116, v111, v115
	s_waitcnt lgkmcnt(0)
	v_add_f32_e32 v115, v115, v116
	ds_bpermute_b32 v116, v112, v115
	s_branch .LBB0_938

; #define LAS __attribute__((address_space(3)))
; __device__ __forceinline__ float sum4(f32x4 v) { return (v.x + v.y) + (v.z + v.w); }
; __device__ __forceinline__ float dot4(f32x4 v) { return (v.x * v.x + v.y * v.y) + (v.z * v.z + v.w * v.w); }
; __device__ __forceinline__ float quad_sum(float t, int lane) { t += shx(t, 16, lane); t += shx(t, 32, lane); return t; }
;     template <int A0, int A1> __device__ __forceinline__ void run(const f32x4 (&acc)[2][2][4][2], const Unit& u, int wr, int wc, int fr, int fq) const {
;     ...
; #pragma unroll
;             for (int m = 0; m < 4; ++m) {
;                 const int row = row0 + ai * 128 + m * 16;
;                 const float t = quad_sum(sum4(*(const f32x4*)(ssqp + (size_t)row * 16 + 4 * fq)), fq * 16 + fr);
;                 const float rr = rsqrtf(t * (1.0f / 1024.0f) + EPS);
;                 f32x4 v[2][2];
; #pragma unroll
;                 for (int bj = 0; bj < 2; ++bj)
; #pragma unroll
;                     for (int n = 0; n < 2; ++n) v[bj][n] = acc[ai][bj][m][n] * rr + b[bj][n];
;                 if (u.pn == 0) {
;                     const float q = quad_sum((dot4(v[0][0]) + dot4(v[0][1])) + (dot4(v[1][0]) + dot4(v[1][1])), fq * 16 + fr);
;                     if (fq == 0) ssqq[(size_t)row * 4 + wc] = q;
;                 } else if (u.pn == 1) {
;                     const float q = quad_sum(dot4(v[0][0]) + dot4(v[0][1]), fq * 16 + fr);
; template <class Epi, int AI>
; __device__ __forceinline__ void skinny_item(LAS unsigned char* lds, const Gemm g, const Epi& E, const Unit u, int wr, int wc, int wave, int lane) {
;     ...
; #pragma unroll 1
;         for (int w = 0; w < 7; ++w) {
; #pragma unroll
;             for (int bj = 0; bj < 2; ++bj)
; #pragma unroll
;                 for (int m = 0; m < 4; ++m)
; #pragma unroll
;                     for (int n = 0; n < 2; ++n) acc[AI][bj][m][n] += *(const LAS f32x4*)(lds + ((w * 16 + bj * 8 + m * 2 + n) * 64 + lane) * 16);
;         }
.LBB0_993:
	v_add_u32_e32 v56, s6, v81
	ds_read_b128 v[190:193], v56
	ds_read_b128 v[194:197], v56 offset:1024
	ds_read_b128 v[198:201], v56 offset:2048
	ds_read_b128 v[202:205], v56 offset:3072
	ds_read_b128 v[206:209], v56 offset:4096
	ds_read_b128 v[210:213], v56 offset:5120
	ds_read_b128 v[214:217], v56 offset:6144
	ds_read_b128 v[218:221], v56 offset:7168
	ds_read_b128 v[222:225], v56 offset:8192
	ds_read_b128 v[226:229], v56 offset:9216
	ds_read_b128 v[230:233], v56 offset:10240
	ds_read_b128 v[234:237], v56 offset:11264
	ds_read_b128 v[240:243], v56 offset:12288
	ds_read_b128 v[244:247], v56 offset:13312
	ds_read_b128 v[248:251], v56 offset:14336
	ds_read_b128 v[48:51], v56 offset:15360
	s_waitcnt lgkmcnt(0)
	v_pk_add_f32 v[66:67], v[66:67], v[192:193]
	v_pk_add_f32 v[64:65], v[64:65], v[190:191]
	v_pk_add_f32 v[70:71], v[70:71], v[196:197]
	v_pk_add_f32 v[68:69], v[68:69], v[194:195]
	v_pk_add_f32 v[46:47], v[46:47], v[200:201]
	v_pk_add_f32 v[44:45], v[44:45], v[198:199]
	v_pk_add_f32 v[42:43], v[42:43], v[204:205]
	v_pk_add_f32 v[40:41], v[40:41], v[202:203]
	v_pk_add_f32 v[30:31], v[30:31], v[208:209]
	v_pk_add_f32 v[28:29], v[28:29], v[206:207]
	v_pk_add_f32 v[26:27], v[26:27], v[212:213]
	v_pk_add_f32 v[24:25], v[24:25], v[210:211]
	v_pk_add_f32 v[14:15], v[14:15], v[216:217]
	v_pk_add_f32 v[12:13], v[12:13], v[214:215]
	v_pk_add_f32 v[10:11], v[10:11], v[220:221]
	v_pk_add_f32 v[8:9], v[8:9], v[218:219]
	v_pk_add_f32 v[54:55], v[54:55], v[224:225]
	v_pk_add_f32 v[52:53], v[52:53], v[222:223]
	v_pk_add_f32 v[62:63], v[62:63], v[228:229]
	v_pk_add_f32 v[60:61], v[60:61], v[226:227]
	v_pk_add_f32 v[38:39], v[38:39], v[232:233]
	v_pk_add_f32 v[36:37], v[36:37], v[230:231]
	v_pk_add_f32 v[34:35], v[34:35], v[236:237]
	v_pk_add_f32 v[32:33], v[32:33], v[234:235]
	v_pk_add_f32 v[22:23], v[22:23], v[242:243]
	v_pk_add_f32 v[20:21], v[20:21], v[240:241]
	v_pk_add_f32 v[18:19], v[18:19], v[246:247]
	v_pk_add_f32 v[16:17], v[16:17], v[244:245]
	v_pk_add_f32 v[6:7], v[6:7], v[250:251]
	v_pk_add_f32 v[4:5], v[4:5], v[248:249]
	v_pk_add_f32 v[2:3], v[2:3], v[50:51]
	v_pk_add_f32 v[0:1], v[0:1], v[48:49]
	s_addk_i32 s6, 0x4000
	s_cmp_lg_u32 s6, 0x1c000
	s_cbranch_scc1 .LBB0_993
	v_lshlrev_b32_e32 v128, 6, v114
	v_lshl_add_u64 v[48:49], v[84:85], 0, v[128:129]
	global_load_dwordx4 v[48:51], v[48:49], off
	s_add_i32 s26, s26, s27
	v_add_u32_e32 v90, s26, v80
	v_ashrrev_i32_e32 v91, 31, v90
	s_cmp_lt_i32 s38, 1
	s_waitcnt vmcnt(0)
	v_mov_b32_e32 v56, v49
	v_mov_b32_e32 v57, v50
	v_mov_b32_e32 v49, v51
	v_pk_add_f32 v[48:49], v[56:57], v[48:49]
	v_lshl_add_u64 v[56:57], v[90:91], 2, s[8:9]
	v_add_f32_e32 v48, v48, v49
	ds_bpermute_b32 v49, v111, v48
	s_waitcnt lgkmcnt(0)
	v_add_f32_e32 v92, v48, v49
	global_load_dwordx4 v[76:79], v[56:57], off
	global_load_dwordx4 v[72:75], v[56:57], off offset:16
	global_load_dwordx4 v[48:51], v[56:57], off offset:528
	s_nop 0
	global_load_dwordx4 v[56:59], v[56:57], off offset:512
	ds_bpermute_b32 v115, v112, v92
	s_waitcnt lgkmcnt(0)
	v_add_f32_e32 v92, v92, v115
	v_fmamk_f32 v92, v92, 0x3a800000, v252
	v_mul_f32_e32 v115, 0x4b800000, v92
	v_cmp_gt_f32_e32 vcc, s49, v92
	s_nop 1
	v_cndmask_b32_e32 v92, v92, v115, vcc
	v_rsq_f32_e32 v92, v92
	s_nop 0
	v_mul_f32_e32 v115, 0x45800000, v92
	v_cndmask_b32_e32 v92, v92, v115, vcc
	s_waitcnt vmcnt(3)
	v_pk_fma_f32 v[64:65], v[64:65], v[92:93], v[76:77] op_sel_hi:[1,0,1]
	v_pk_fma_f32 v[66:67], v[66:67], v[92:93], v[78:79] op_sel_hi:[1,0,1]
	s_waitcnt vmcnt(2)
	v_pk_fma_f32 v[68:69], v[68:69], v[92:93], v[72:73] op_sel_hi:[1,0,1]
	v_pk_fma_f32 v[70:71], v[70:71], v[92:93], v[74:75] op_sel_hi:[1,0,1]
	s_cbranch_scc1 .LBB0_997
	s_mov_b64 s[10:11], 0
	s_cmp_eq_u32 s38, 1
	s_mov_b64 s[6:7], 0
	s_cbranch_scc0 .LBB0_998
	v_mov_b32_e32 v118, v65
	v_mov_b32_e32 v119, v69
	v_mov_b32_e32 v116, v64
	v_mov_b32_e32 v117, v68
	v_pk_mul_f32 v[118:119], v[118:119], v[118:119]
	v_mov_b32_e32 v120, v67
	v_mov_b32_e32 v121, v71
	v_pk_fma_f32 v[116:117], v[116:117], v[116:117], v[118:119]
	v_mov_b32_e32 v118, v66
	v_mov_b32_e32 v119, v70
	v_pk_mul_f32 v[120:121], v[120:121], v[120:121]
	s_and_b64 s[6:7], s[4:5], exec
	v_pk_fma_f32 v[118:119], v[118:119], v[118:119], v[120:121]
	s_nop 0
	v_pk_add_f32 v[116:117], v[116:117], v[118:119]
	s_nop 0
	v_add_f32_e32 v115, v116, v117
	ds_bpermute_b32 v116, v111, v115
	s_waitcnt lgkmcnt(0)
	v_add_f32_e32 v115, v115, v116
	ds_bpermute_b32 v116, v112, v115
	s_branch .LBB0_998

; #define LAS __attribute__((address_space(3)))
; __device__ __forceinline__ float sum4(f32x4 v) { return (v.x + v.y) + (v.z + v.w); }
; __device__ __forceinline__ float dot4(f32x4 v) { return (v.x * v.x + v.y * v.y) + (v.z * v.z + v.w * v.w); }
; __device__ __forceinline__ float quad_sum(float t, int lane) { t += shx(t, 16, lane); t += shx(t, 32, lane); return t; }
;     template <int A0, int A1> __device__ __forceinline__ void run(const f32x4 (&acc)[2][2][4][2], const Unit& u, int wr, int wc, int fr, int fq) const {
;     ...
; #pragma unroll
;             for (int m = 0; m < 4; ++m) {
;                 const int row = row0 + ai * 128 + m * 16;
;                 const float t = quad_sum(sum4(*(const f32x4*)(ssqp + (size_t)row * 16 + 4 * fq)), fq * 16 + fr);
;                 const float rr = rsqrtf(t * (1.0f / 1024.0f) + EPS);
;                 f32x4 v[2][2];
; #pragma unroll
;                 for (int bj = 0; bj < 2; ++bj)
; #pragma unroll
;                     for (int n = 0; n < 2; ++n) v[bj][n] = acc[ai][bj][m][n] * rr + b[bj][n];
;                 if (u.pn == 0) {
;                     const float q = quad_sum((dot4(v[0][0]) + dot4(v[0][1])) + (dot4(v[1][0]) + dot4(v[1][1])), fq * 16 + fr);
;                     if (fq == 0) ssqq[(size_t)row * 4 + wc] = q;
;                 } else if (u.pn == 1) {
;                     const float q = quad_sum(dot4(v[0][0]) + dot4(v[0][1]), fq * 16 + fr);
; template <class Epi, int AI>
; __device__ __forceinline__ void skinny_item(LAS unsigned char* lds, const Gemm g, const Epi& E, const Unit u, int wr, int wc, int wave, int lane) {
;     ...
; #pragma unroll 1
;         for (int w = 0; w < 7; ++w) {
; #pragma unroll
;             for (int bj = 0; bj < 2; ++bj)
; #pragma unroll
;                 for (int m = 0; m < 4; ++m)
; #pragma unroll
;                     for (int n = 0; n < 2; ++n) acc[AI][bj][m][n] += *(const LAS f32x4*)(lds + ((w * 16 + bj * 8 + m * 2 + n) * 64 + lane) * 16);
;         }
.LBB0_1061:
	v_add_u32_e32 v68, s8, v81
	ds_read_b128 v[190:193], v68
	ds_read_b128 v[194:197], v68 offset:1024
	ds_read_b128 v[198:201], v68 offset:2048
	ds_read_b128 v[202:205], v68 offset:3072
	ds_read_b128 v[206:209], v68 offset:4096
	ds_read_b128 v[210:213], v68 offset:5120
	ds_read_b128 v[214:217], v68 offset:6144
	ds_read_b128 v[218:221], v68 offset:7168
	ds_read_b128 v[222:225], v68 offset:8192
	ds_read_b128 v[226:229], v68 offset:9216
	ds_read_b128 v[230:233], v68 offset:10240
	ds_read_b128 v[234:237], v68 offset:11264
	ds_read_b128 v[240:243], v68 offset:12288
	ds_read_b128 v[244:247], v68 offset:13312
	ds_read_b128 v[248:251], v68 offset:14336
	ds_read_b128 v[64:67], v68 offset:15360
	s_waitcnt lgkmcnt(0)
	v_pk_add_f32 v[58:59], v[58:59], v[192:193]
	v_pk_add_f32 v[56:57], v[56:57], v[190:191]
	v_pk_add_f32 v[62:63], v[62:63], v[196:197]
	v_pk_add_f32 v[60:61], v[60:61], v[194:195]
	v_pk_add_f32 v[46:47], v[46:47], v[200:201]
	v_pk_add_f32 v[44:45], v[44:45], v[198:199]
	v_pk_add_f32 v[42:43], v[42:43], v[204:205]
	v_pk_add_f32 v[40:41], v[40:41], v[202:203]
	v_pk_add_f32 v[30:31], v[30:31], v[208:209]
	v_pk_add_f32 v[28:29], v[28:29], v[206:207]
	v_pk_add_f32 v[26:27], v[26:27], v[212:213]
	v_pk_add_f32 v[24:25], v[24:25], v[210:211]
	v_pk_add_f32 v[14:15], v[14:15], v[216:217]
	v_pk_add_f32 v[12:13], v[12:13], v[214:215]
	v_pk_add_f32 v[10:11], v[10:11], v[220:221]
	v_pk_add_f32 v[8:9], v[8:9], v[218:219]
	v_pk_add_f32 v[50:51], v[50:51], v[224:225]
	v_pk_add_f32 v[48:49], v[48:49], v[222:223]
	v_pk_add_f32 v[54:55], v[54:55], v[228:229]
	v_pk_add_f32 v[52:53], v[52:53], v[226:227]
	v_pk_add_f32 v[38:39], v[38:39], v[232:233]
	v_pk_add_f32 v[36:37], v[36:37], v[230:231]
	v_pk_add_f32 v[34:35], v[34:35], v[236:237]
	v_pk_add_f32 v[32:33], v[32:33], v[234:235]
	v_pk_add_f32 v[22:23], v[22:23], v[242:243]
	v_pk_add_f32 v[20:21], v[20:21], v[240:241]
	v_pk_add_f32 v[18:19], v[18:19], v[246:247]
	v_pk_add_f32 v[16:17], v[16:17], v[244:245]
	v_pk_add_f32 v[6:7], v[6:7], v[250:251]
	v_pk_add_f32 v[4:5], v[4:5], v[248:249]
	v_pk_add_f32 v[2:3], v[2:3], v[66:67]
	v_pk_add_f32 v[0:1], v[0:1], v[64:65]
	s_addk_i32 s8, 0x4000
	s_cmp_lg_u32 s8, 0x1c000
	s_cbranch_scc1 .LBB0_1061
	v_lshlrev_b32_e32 v128, 6, v114
	v_lshl_add_u64 v[64:65], v[84:85], 0, v[128:129]
	global_load_dwordx4 v[64:67], v[64:65], off
	s_add_i32 s8, s26, s27
	v_add_u32_e32 v90, s8, v80
	v_ashrrev_i32_e32 v91, 31, v90
	s_cmp_gt_i32 s36, -1
	s_waitcnt vmcnt(0)
	v_mov_b32_e32 v68, v65
	v_mov_b32_e32 v69, v66
	v_mov_b32_e32 v65, v67
	v_pk_add_f32 v[64:65], v[68:69], v[64:65]
	v_lshl_add_u64 v[68:69], v[90:91], 2, s[10:11]
	v_add_f32_e32 v64, v64, v65
	ds_bpermute_b32 v65, v111, v64
	s_waitcnt lgkmcnt(0)
	v_add_f32_e32 v92, v64, v65
	global_load_dwordx4 v[76:79], v[68:69], off
	global_load_dwordx4 v[72:75], v[68:69], off offset:16
	global_load_dwordx4 v[64:67], v[68:69], off offset:528
	s_nop 0
	global_load_dwordx4 v[68:71], v[68:69], off offset:512
	ds_bpermute_b32 v115, v112, v92
	s_waitcnt lgkmcnt(0)
	v_add_f32_e32 v92, v92, v115
	v_fmamk_f32 v92, v92, 0x3a800000, v252
	v_mul_f32_e32 v115, 0x4b800000, v92
	v_cmp_gt_f32_e32 vcc, s49, v92
	s_nop 1
	v_cndmask_b32_e32 v92, v92, v115, vcc
	v_rsq_f32_e32 v92, v92
	s_nop 0
	v_mul_f32_e32 v115, 0x45800000, v92
	v_cndmask_b32_e32 v92, v92, v115, vcc
	s_waitcnt vmcnt(3)
	v_pk_fma_f32 v[56:57], v[56:57], v[92:93], v[76:77] op_sel_hi:[1,0,1]
	v_pk_fma_f32 v[58:59], v[58:59], v[92:93], v[78:79] op_sel_hi:[1,0,1]
	s_waitcnt vmcnt(2)
	v_pk_fma_f32 v[60:61], v[60:61], v[92:93], v[72:73] op_sel_hi:[1,0,1]
	v_pk_fma_f32 v[62:63], v[62:63], v[92:93], v[74:75] op_sel_hi:[1,0,1]
	s_cbranch_scc0 .LBB0_1064
	v_mov_b32_e32 v118, v57
	v_mov_b32_e32 v119, v61
	v_mov_b32_e32 v116, v56
	v_mov_b32_e32 v117, v60
	v_pk_mul_f32 v[118:119], v[118:119], v[118:119]
	v_mov_b32_e32 v120, v59
	v_mov_b32_e32 v121, v63
	v_pk_fma_f32 v[116:117], v[116:117], v[116:117], v[118:119]
	v_mov_b32_e32 v118, v58
	v_mov_b32_e32 v119, v62
	v_pk_mul_f32 v[120:121], v[120:121], v[120:121]
	s_mov_b64 s[16:17], 0
	v_pk_fma_f32 v[118:119], v[118:119], v[118:119], v[120:121]
	s_and_b64 s[8:9], s[4:5], exec
	v_pk_add_f32 v[116:117], v[116:117], v[118:119]
	s_nop 0
	v_add_f32_e32 v115, v116, v117
	ds_bpermute_b32 v116, v111, v115
	s_waitcnt lgkmcnt(0)
	v_add_f32_e32 v115, v115, v116
	ds_bpermute_b32 v116, v112, v115
	s_branch .LBB0_1065

; #define LAS __attribute__((address_space(3)))
; __device__ __forceinline__ float sum4(f32x4 v) { return (v.x + v.y) + (v.z + v.w); }
; __device__ __forceinline__ float dot4(f32x4 v) { return (v.x * v.x + v.y * v.y) + (v.z * v.z + v.w * v.w); }
; __device__ __forceinline__ float quad_sum(float t, int lane) { t += shx(t, 16, lane); t += shx(t, 32, lane); return t; }
;     template <int A0, int A1> __device__ __forceinline__ void run(const f32x4 (&acc)[2][2][4][2], const Unit& u, int wr, int wc, int fr, int fq) const {
;     ...
; #pragma unroll
;             for (int m = 0; m < 4; ++m) {
;                 const int row = row0 + ai * 128 + m * 16;
;                 const float t = quad_sum(sum4(*(const f32x4*)(ssqp + (size_t)row * 16 + 4 * fq)), fq * 16 + fr);
;                 const float rr = rsqrtf(t * (1.0f / 1024.0f) + EPS);
;                 f32x4 v[2][2];
; #pragma unroll
;                 for (int bj = 0; bj < 2; ++bj)
; #pragma unroll
;                     for (int n = 0; n < 2; ++n) v[bj][n] = acc[ai][bj][m][n] * rr + b[bj][n];
;                 if (u.pn == 0) {
;                     const float q = quad_sum((dot4(v[0][0]) + dot4(v[0][1])) + (dot4(v[1][0]) + dot4(v[1][1])), fq * 16 + fr);
;                     if (fq == 0) ssqq[(size_t)row * 4 + wc] = q;
;                 } else if (u.pn == 1) {
;                     const float q = quad_sum(dot4(v[0][0]) + dot4(v[0][1]), fq * 16 + fr);
; template <class Epi, int AI>
; __device__ __forceinline__ void skinny_item(LAS unsigned char* lds, const Gemm g, const Epi& E, const Unit u, int wr, int wc, int wave, int lane) {
;     ...
; #pragma unroll 1
;         for (int w = 0; w < 7; ++w) {
; #pragma unroll
;             for (int bj = 0; bj < 2; ++bj)
; #pragma unroll
;                 for (int m = 0; m < 4; ++m)
; #pragma unroll
;                     for (int n = 0; n < 2; ++n) acc[AI][bj][m][n] += *(const LAS f32x4*)(lds + ((w * 16 + bj * 8 + m * 2 + n) * 64 + lane) * 16);
;         }
.LBB0_1118:
	v_add_u32_e32 v68, s6, v81
	ds_read_b128 v[190:193], v68
	ds_read_b128 v[194:197], v68 offset:1024
	ds_read_b128 v[198:201], v68 offset:2048
	ds_read_b128 v[202:205], v68 offset:3072
	ds_read_b128 v[206:209], v68 offset:4096
	ds_read_b128 v[210:213], v68 offset:5120
	ds_read_b128 v[214:217], v68 offset:6144
	ds_read_b128 v[218:221], v68 offset:7168
	ds_read_b128 v[222:225], v68 offset:8192
	ds_read_b128 v[226:229], v68 offset:9216
	ds_read_b128 v[230:233], v68 offset:10240
	ds_read_b128 v[234:237], v68 offset:11264
	ds_read_b128 v[240:243], v68 offset:12288
	ds_read_b128 v[244:247], v68 offset:13312
	ds_read_b128 v[248:251], v68 offset:14336
	ds_read_b128 v[64:67], v68 offset:15360
	s_waitcnt lgkmcnt(0)
	v_pk_add_f32 v[58:59], v[58:59], v[192:193]
	v_pk_add_f32 v[56:57], v[56:57], v[190:191]
	v_pk_add_f32 v[62:63], v[62:63], v[196:197]
	v_pk_add_f32 v[60:61], v[60:61], v[194:195]
	v_pk_add_f32 v[46:47], v[46:47], v[200:201]
	v_pk_add_f32 v[44:45], v[44:45], v[198:199]
	v_pk_add_f32 v[42:43], v[42:43], v[204:205]
	v_pk_add_f32 v[40:41], v[40:41], v[202:203]
	v_pk_add_f32 v[30:31], v[30:31], v[208:209]
	v_pk_add_f32 v[28:29], v[28:29], v[206:207]
	v_pk_add_f32 v[26:27], v[26:27], v[212:213]
	v_pk_add_f32 v[24:25], v[24:25], v[210:211]
	v_pk_add_f32 v[14:15], v[14:15], v[216:217]
	v_pk_add_f32 v[12:13], v[12:13], v[214:215]
	v_pk_add_f32 v[10:11], v[10:11], v[220:221]
	v_pk_add_f32 v[8:9], v[8:9], v[218:219]
	v_pk_add_f32 v[50:51], v[50:51], v[224:225]
	v_pk_add_f32 v[48:49], v[48:49], v[222:223]
	v_pk_add_f32 v[54:55], v[54:55], v[228:229]
	v_pk_add_f32 v[52:53], v[52:53], v[226:227]
	v_pk_add_f32 v[38:39], v[38:39], v[232:233]
	v_pk_add_f32 v[36:37], v[36:37], v[230:231]
	v_pk_add_f32 v[34:35], v[34:35], v[236:237]
	v_pk_add_f32 v[32:33], v[32:33], v[234:235]
	v_pk_add_f32 v[22:23], v[22:23], v[242:243]
	v_pk_add_f32 v[20:21], v[20:21], v[240:241]
	v_pk_add_f32 v[18:19], v[18:19], v[246:247]
	v_pk_add_f32 v[16:17], v[16:17], v[244:245]
	v_pk_add_f32 v[6:7], v[6:7], v[250:251]
	v_pk_add_f32 v[4:5], v[4:5], v[248:249]
	v_pk_add_f32 v[2:3], v[2:3], v[66:67]
	v_pk_add_f32 v[0:1], v[0:1], v[64:65]
	s_addk_i32 s6, 0x4000
	s_cmp_lg_u32 s6, 0x1c000
	s_cbranch_scc1 .LBB0_1118
	v_lshlrev_b32_e32 v128, 6, v114
	v_lshl_add_u64 v[64:65], v[84:85], 0, v[128:129]
	global_load_dwordx4 v[64:67], v[64:65], off
	s_add_i32 s26, s26, s27
	v_add_u32_e32 v90, s26, v80
	v_ashrrev_i32_e32 v91, 31, v90
	s_cmp_gt_i32 s36, -1
	s_waitcnt vmcnt(0)
	v_mov_b32_e32 v68, v65
	v_mov_b32_e32 v69, v66
	v_mov_b32_e32 v65, v67
	v_pk_add_f32 v[64:65], v[68:69], v[64:65]
	v_lshl_add_u64 v[68:69], v[90:91], 2, s[10:11]
	v_add_f32_e32 v64, v64, v65
	ds_bpermute_b32 v65, v111, v64
	s_waitcnt lgkmcnt(0)
	v_add_f32_e32 v92, v64, v65
	global_load_dwordx4 v[76:79], v[68:69], off
	global_load_dwordx4 v[72:75], v[68:69], off offset:16
	global_load_dwordx4 v[64:67], v[68:69], off offset:528
	s_nop 0
	global_load_dwordx4 v[68:71], v[68:69], off offset:512
	ds_bpermute_b32 v115, v112, v92
	s_waitcnt lgkmcnt(0)
	v_add_f32_e32 v92, v92, v115
	v_fmamk_f32 v92, v92, 0x3a800000, v252
	v_mul_f32_e32 v115, 0x4b800000, v92
	v_cmp_gt_f32_e32 vcc, s49, v92
	s_nop 1
	v_cndmask_b32_e32 v92, v92, v115, vcc
	v_rsq_f32_e32 v92, v92
	s_nop 0
	v_mul_f32_e32 v115, 0x45800000, v92
	v_cndmask_b32_e32 v92, v92, v115, vcc
	s_waitcnt vmcnt(3)
	v_pk_fma_f32 v[56:57], v[56:57], v[92:93], v[76:77] op_sel_hi:[1,0,1]
	v_pk_fma_f32 v[58:59], v[58:59], v[92:93], v[78:79] op_sel_hi:[1,0,1]
	s_waitcnt vmcnt(2)
	v_pk_fma_f32 v[60:61], v[60:61], v[92:93], v[72:73] op_sel_hi:[1,0,1]
	v_pk_fma_f32 v[62:63], v[62:63], v[92:93], v[74:75] op_sel_hi:[1,0,1]
	s_cbranch_scc0 .LBB0_1121
	v_mov_b32_e32 v118, v57
	v_mov_b32_e32 v119, v61
	v_mov_b32_e32 v116, v56
	v_mov_b32_e32 v117, v60
	v_pk_mul_f32 v[118:119], v[118:119], v[118:119]
	v_mov_b32_e32 v120, v59
	v_mov_b32_e32 v121, v63
	v_pk_fma_f32 v[116:117], v[116:117], v[116:117], v[118:119]
	v_mov_b32_e32 v118, v58
	v_mov_b32_e32 v119, v62
	v_pk_mul_f32 v[120:121], v[120:121], v[120:121]
	s_mov_b64 s[8:9], 0
	v_pk_fma_f32 v[118:119], v[118:119], v[118:119], v[120:121]
	s_and_b64 s[6:7], s[4:5], exec
	v_pk_add_f32 v[116:117], v[116:117], v[118:119]
	s_nop 0
	v_add_f32_e32 v115, v116, v117
	ds_bpermute_b32 v116, v111, v115
	s_waitcnt lgkmcnt(0)
	v_add_f32_e32 v115, v115, v116
	ds_bpermute_b32 v116, v112, v115
	s_branch .LBB0_1122

; #define LAS __attribute__((address_space(3)))
;     template <int A0, int A1> __device__ __forceinline__ void run(const f32x4 (&acc)[2][2][4][2], const Unit& u, int wr, int wc, int fr, int fq) const {
;     ...
;         for (int bj = 0; bj < 2; ++bj) {
;             const int col = u.pn * 256 + bj * 128 + wc * 32 + fq * 8;
;             const f32x4 gv0 = *(const f32x4*)(gate + s * NMOD + col) * gmul, gv1 = *(const f32x4*)(gate + s * NMOD + col + 4) * gmul;
;             f32x4 wv0 = (f32x4){0.f, 0.f, 0.f, 0.f}, wv1 = wv0;
;             if (has_next) { wv0 = *(const f32x4*)(nw + col) * (*(const f32x4*)(nscale + s * NMOD + col) + 1.0f); wv1 = *(const f32x4*)(nw + col + 4) * (*(const f32x4*)(nscale + s * NMOD + col + 4) + 1.0f); }
; #pragma unroll
;             for (int ai = A0; ai < A1; ++ai)
; #pragma unroll
;                 for (int m = 0; m < 4; ++m) {
;                     const size_t off = (size_t)(row0 + ai * 128 + m * 16) * DM + col;
;                     const f32x4 x0 = *(const f32x4*)(xo + off) + gv0 * acc[ai][bj][m][0];
; template <class Epi, int AI>
; __device__ __forceinline__ void skinny_item(LAS unsigned char* lds, const Gemm g, const Epi& E, const Unit u, int wr, int wc, int wave, int lane) {
;     ...
;         for (int w = 0; w < 7; ++w) {
; #pragma unroll
;             for (int bj = 0; bj < 2; ++bj)
; #pragma unroll
;                 for (int m = 0; m < 4; ++m)
; #pragma unroll
;                     for (int n = 0; n < 2; ++n) acc[AI][bj][m][n] += *(const LAS f32x4*)(lds + ((w * 16 + bj * 8 + m * 2 + n) * 64 + lane) * 16);
;         }
.LBB0_1414:
	s_andn2_b64 vcc, exec, s[60:61]
	s_waitcnt lgkmcnt(0)
	s_barrier
	s_cbranch_vccnz .LBB0_1446
	s_mov_b32 s8, 0
	s_or_b32 vcc_lo, s39, s39
	v_add_u32_e32 v248, vcc_lo, v72
	v_ashrrev_i32_e32 v249, 31, v248
	v_lshlrev_b32_e32 v250, 10, v134
	v_mov_b32_e32 v251, 0
	v_lshl_add_u64 v[248:249], v[250:251], 0, v[248:249]
	v_lshlrev_b64 v[248:249], 2, v[248:249]
	v_lshl_add_u64 v[248:249], s[26:27], 0, v[248:249]
	v_mov_b32_e32 v250, 0x10000
	global_load_dword v253, v[248:249], off
	global_load_dword v253, v[248:249], off offset:512
	v_lshl_add_u64 v[248:249], v[248:249], 0, v[250:251]
	global_load_dword v253, v[248:249], off
	global_load_dword v253, v[248:249], off offset:512
	v_lshl_add_u64 v[248:249], v[248:249], 0, v[250:251]
	global_load_dword v253, v[248:249], off
	global_load_dword v253, v[248:249], off offset:512
	v_lshl_add_u64 v[248:249], v[248:249], 0, v[250:251]
	global_load_dword v253, v[248:249], off
	global_load_dword v253, v[248:249], off offset:512
.LBB0_1416:
	v_add_u32_e32 v68, s8, v109
	ds_read_b128 v[190:193], v68
	ds_read_b128 v[194:197], v68 offset:1024
	ds_read_b128 v[198:201], v68 offset:2048
	ds_read_b128 v[202:205], v68 offset:3072
	ds_read_b128 v[206:209], v68 offset:4096
	ds_read_b128 v[210:213], v68 offset:5120
	ds_read_b128 v[214:217], v68 offset:6144
	ds_read_b128 v[218:221], v68 offset:7168
	ds_read_b128 v[222:225], v68 offset:8192
	ds_read_b128 v[226:229], v68 offset:9216
	ds_read_b128 v[230:233], v68 offset:10240
	ds_read_b128 v[234:237], v68 offset:11264
	ds_read_b128 v[240:243], v68 offset:12288
	ds_read_b128 v[244:247], v68 offset:13312
	ds_read_b128 v[248:251], v68 offset:14336
	ds_read_b128 v[64:67], v68 offset:15360
	s_waitcnt lgkmcnt(0)
	v_pk_add_f32 v[58:59], v[58:59], v[192:193]
	v_pk_add_f32 v[56:57], v[56:57], v[190:191]
	v_pk_add_f32 v[62:63], v[62:63], v[196:197]
	v_pk_add_f32 v[60:61], v[60:61], v[194:195]
	v_pk_add_f32 v[54:55], v[54:55], v[200:201]
	v_pk_add_f32 v[52:53], v[52:53], v[198:199]
	v_pk_add_f32 v[50:51], v[50:51], v[204:205]
	v_pk_add_f32 v[48:49], v[48:49], v[202:203]
	v_pk_add_f32 v[46:47], v[46:47], v[208:209]
	v_pk_add_f32 v[44:45], v[44:45], v[206:207]
	v_pk_add_f32 v[42:43], v[42:43], v[212:213]
	v_pk_add_f32 v[40:41], v[40:41], v[210:211]
	v_pk_add_f32 v[38:39], v[38:39], v[216:217]
	v_pk_add_f32 v[36:37], v[36:37], v[214:215]
	v_pk_add_f32 v[34:35], v[34:35], v[220:221]
	v_pk_add_f32 v[32:33], v[32:33], v[218:219]
	v_pk_add_f32 v[30:31], v[30:31], v[224:225]
	v_pk_add_f32 v[28:29], v[28:29], v[222:223]
	v_pk_add_f32 v[26:27], v[26:27], v[228:229]
	v_pk_add_f32 v[24:25], v[24:25], v[226:227]
	v_pk_add_f32 v[18:19], v[18:19], v[232:233]
	v_pk_add_f32 v[16:17], v[16:17], v[230:231]
	v_pk_add_f32 v[22:23], v[22:23], v[236:237]
	v_pk_add_f32 v[20:21], v[20:21], v[234:235]
	v_pk_add_f32 v[6:7], v[6:7], v[242:243]
	v_pk_add_f32 v[4:5], v[4:5], v[240:241]
	v_pk_add_f32 v[10:11], v[10:11], v[246:247]
	v_pk_add_f32 v[8:9], v[8:9], v[244:245]
	v_pk_add_f32 v[2:3], v[2:3], v[250:251]
	v_pk_add_f32 v[0:1], v[0:1], v[248:249]
	v_pk_add_f32 v[14:15], v[14:15], v[66:67]
	v_pk_add_f32 v[12:13], v[12:13], v[64:65]
	s_addk_i32 s8, 0x4000
	s_cmp_lg_u32 s8, 0x1c000
	s_cbranch_scc1 .LBB0_1416
	v_add_u32_e32 v88, s39, v72
	v_ashrrev_i32_e32 v89, 31, v88
	v_lshl_add_u64 v[68:69], v[88:89], 2, s[76:77]
	global_load_dwordx4 v[64:67], v[68:69], off offset:16
	s_nop 0
	global_load_dwordx4 v[68:71], v[68:69], off
	v_mov_b32_e32 v96, 0
	v_cndmask_b32_e64 v75, 0, 1, s[74:75]
	v_cmp_ne_u32_e64 s[8:9], 1, v75
	s_andn2_b64 vcc, exec, s[74:75]
	v_mov_b32_e32 v97, v96
	v_mov_b32_e32 v98, v96
	v_mov_b32_e32 v99, v96
	v_mov_b32_e32 v100, v96
	v_mov_b32_e32 v101, v96
	v_mov_b32_e32 v102, v96
	v_mov_b32_e32 v103, v96
	s_cbranch_vccnz .LBB0_1419
	v_lshlrev_b64 v[98:99], 2, v[88:89]
	v_lshl_add_u64 v[94:95], s[78:79], 0, v[98:99]
	global_load_dwordx4 v[90:93], v[94:95], off
	s_nop 0
	global_load_dwordx4 v[94:97], v[94:95], off offset:16
	v_lshl_add_u64 v[102:103], s[16:17], 0, v[98:99]
	global_load_dwordx4 v[98:101], v[102:103], off
	global_load_dwordx4 v[104:107], v[102:103], off offset:16
	s_waitcnt vmcnt(3)
	v_pk_add_f32 v[92:93], v[92:93], 1.0 op_sel_hi:[1,0]
	v_pk_add_f32 v[90:91], v[90:91], 1.0 op_sel_hi:[1,0]
	s_waitcnt vmcnt(2)
	v_pk_add_f32 v[96:97], v[96:97], 1.0 op_sel_hi:[1,0]
	v_pk_add_f32 v[94:95], v[94:95], 1.0 op_sel_hi:[1,0]
	s_waitcnt vmcnt(1)
	v_pk_mul_f32 v[102:103], v[100:101], v[92:93]
	v_pk_mul_f32 v[100:101], v[98:99], v[90:91]
	s_waitcnt vmcnt(0)
	v_pk_mul_f32 v[98:99], v[106:107], v[96:97]
	v_pk_mul_f32 v[96:97], v[104:105], v[94:95]

; #define LAS __attribute__((address_space(3)))
;     template <int A0, int A1> __device__ __forceinline__ void run(const f32x4 (&acc)[2][2][4][2], const Unit& u, int wr, int wc, int fr, int fq) const {
;     ...
;         for (int bj = 0; bj < 2; ++bj) {
;             const int col = u.pn * 256 + bj * 128 + wc * 32 + fq * 8;
;             const f32x4 gv0 = *(const f32x4*)(gate + s * NMOD + col) * gmul, gv1 = *(const f32x4*)(gate + s * NMOD + col + 4) * gmul;
;             f32x4 wv0 = (f32x4){0.f, 0.f, 0.f, 0.f}, wv1 = wv0;
;             if (has_next) { wv0 = *(const f32x4*)(nw + col) * (*(const f32x4*)(nscale + s * NMOD + col) + 1.0f); wv1 = *(const f32x4*)(nw + col + 4) * (*(const f32x4*)(nscale + s * NMOD + col + 4) + 1.0f); }
; #pragma unroll
;             for (int ai = A0; ai < A1; ++ai)
; #pragma unroll
;                 for (int m = 0; m < 4; ++m) {
;                     const size_t off = (size_t)(row0 + ai * 128 + m * 16) * DM + col;
;                     const f32x4 x0 = *(const f32x4*)(xo + off) + gv0 * acc[ai][bj][m][0];
; template <class Epi, int AI>
; __device__ __forceinline__ void skinny_item(LAS unsigned char* lds, const Gemm g, const Epi& E, const Unit u, int wr, int wc, int wave, int lane) {
;     ...
;         for (int w = 0; w < 7; ++w) {
; #pragma unroll
;             for (int bj = 0; bj < 2; ++bj)
; #pragma unroll
;                 for (int m = 0; m < 4; ++m)
; #pragma unroll
;                     for (int n = 0; n < 2; ++n) acc[AI][bj][m][n] += *(const LAS f32x4*)(lds + ((w * 16 + bj * 8 + m * 2 + n) * 64 + lane) * 16);
;         }
.LBB0_1453:
	s_andn2_b64 vcc, exec, s[60:61]
	s_waitcnt lgkmcnt(0)
	s_barrier
	s_cbranch_vccnz .LBB0_1406
	s_mov_b32 s6, 0
	s_or_b32 vcc_lo, s39, s39
	v_add_u32_e32 v248, vcc_lo, v72
	v_ashrrev_i32_e32 v249, 31, v248
	v_lshlrev_b32_e32 v250, 10, v134
	v_mov_b32_e32 v251, 0
	v_lshl_add_u64 v[248:249], v[250:251], 0, v[248:249]
	v_lshlrev_b64 v[248:249], 2, v[248:249]
	v_lshl_add_u64 v[248:249], s[26:27], 0, v[248:249]
	v_mov_b32_e32 v250, 0x10000
	global_load_dword v253, v[248:249], off
	global_load_dword v253, v[248:249], off offset:512
	v_lshl_add_u64 v[248:249], v[248:249], 0, v[250:251]
	global_load_dword v253, v[248:249], off
	global_load_dword v253, v[248:249], off offset:512
	v_lshl_add_u64 v[248:249], v[248:249], 0, v[250:251]
	global_load_dword v253, v[248:249], off
	global_load_dword v253, v[248:249], off offset:512
	v_lshl_add_u64 v[248:249], v[248:249], 0, v[250:251]
	global_load_dword v253, v[248:249], off
	global_load_dword v253, v[248:249], off offset:512
.LBB0_1455:
	v_add_u32_e32 v68, s6, v109
	ds_read_b128 v[190:193], v68
	ds_read_b128 v[194:197], v68 offset:1024
	ds_read_b128 v[198:201], v68 offset:2048
	ds_read_b128 v[202:205], v68 offset:3072
	ds_read_b128 v[206:209], v68 offset:4096
	ds_read_b128 v[210:213], v68 offset:5120
	ds_read_b128 v[214:217], v68 offset:6144
	ds_read_b128 v[218:221], v68 offset:7168
	ds_read_b128 v[222:225], v68 offset:8192
	ds_read_b128 v[226:229], v68 offset:9216
	ds_read_b128 v[230:233], v68 offset:10240
	ds_read_b128 v[234:237], v68 offset:11264
	ds_read_b128 v[240:243], v68 offset:12288
	ds_read_b128 v[244:247], v68 offset:13312
	ds_read_b128 v[248:251], v68 offset:14336
	ds_read_b128 v[64:67], v68 offset:15360
	s_waitcnt lgkmcnt(0)
	v_pk_add_f32 v[58:59], v[58:59], v[192:193]
	v_pk_add_f32 v[56:57], v[56:57], v[190:191]
	v_pk_add_f32 v[62:63], v[62:63], v[196:197]
	v_pk_add_f32 v[60:61], v[60:61], v[194:195]
	v_pk_add_f32 v[54:55], v[54:55], v[200:201]
	v_pk_add_f32 v[52:53], v[52:53], v[198:199]
	v_pk_add_f32 v[50:51], v[50:51], v[204:205]
	v_pk_add_f32 v[48:49], v[48:49], v[202:203]
	v_pk_add_f32 v[46:47], v[46:47], v[208:209]
	v_pk_add_f32 v[44:45], v[44:45], v[206:207]
	v_pk_add_f32 v[42:43], v[42:43], v[212:213]
	v_pk_add_f32 v[40:41], v[40:41], v[210:211]
	v_pk_add_f32 v[38:39], v[38:39], v[216:217]
	v_pk_add_f32 v[36:37], v[36:37], v[214:215]
	v_pk_add_f32 v[34:35], v[34:35], v[220:221]
	v_pk_add_f32 v[32:33], v[32:33], v[218:219]
	v_pk_add_f32 v[30:31], v[30:31], v[224:225]
	v_pk_add_f32 v[28:29], v[28:29], v[222:223]
	v_pk_add_f32 v[26:27], v[26:27], v[228:229]
	v_pk_add_f32 v[24:25], v[24:25], v[226:227]
	v_pk_add_f32 v[18:19], v[18:19], v[232:233]
	v_pk_add_f32 v[16:17], v[16:17], v[230:231]
	v_pk_add_f32 v[22:23], v[22:23], v[236:237]
	v_pk_add_f32 v[20:21], v[20:21], v[234:235]
	v_pk_add_f32 v[6:7], v[6:7], v[242:243]
	v_pk_add_f32 v[4:5], v[4:5], v[240:241]
	v_pk_add_f32 v[10:11], v[10:11], v[246:247]
	v_pk_add_f32 v[8:9], v[8:9], v[244:245]
	v_pk_add_f32 v[2:3], v[2:3], v[250:251]
	v_pk_add_f32 v[0:1], v[0:1], v[248:249]
	v_pk_add_f32 v[14:15], v[14:15], v[66:67]
	v_pk_add_f32 v[12:13], v[12:13], v[64:65]
	s_addk_i32 s6, 0x4000
	s_cmp_lg_u32 s6, 0x1c000
	s_cbranch_scc1 .LBB0_1455
	v_add_u32_e32 v88, s39, v72
	v_ashrrev_i32_e32 v89, 31, v88
	v_lshl_add_u64 v[68:69], v[88:89], 2, s[76:77]
	global_load_dwordx4 v[64:67], v[68:69], off offset:16
	s_nop 0
	global_load_dwordx4 v[68:71], v[68:69], off
	v_mov_b32_e32 v96, 0
	v_cndmask_b32_e64 v75, 0, 1, s[74:75]
	v_cmp_ne_u32_e64 s[6:7], 1, v75
	s_andn2_b64 vcc, exec, s[74:75]
	v_mov_b32_e32 v97, v96
	v_mov_b32_e32 v98, v96
	v_mov_b32_e32 v99, v96
	v_mov_b32_e32 v100, v96
	v_mov_b32_e32 v101, v96
	v_mov_b32_e32 v102, v96
	v_mov_b32_e32 v103, v96
	s_cbranch_vccnz .LBB0_1458
	v_lshlrev_b64 v[98:99], 2, v[88:89]
	v_lshl_add_u64 v[94:95], s[78:79], 0, v[98:99]
	global_load_dwordx4 v[90:93], v[94:95], off
	s_nop 0
	global_load_dwordx4 v[94:97], v[94:95], off offset:16
	v_lshl_add_u64 v[102:103], s[16:17], 0, v[98:99]
	global_load_dwordx4 v[98:101], v[102:103], off
	global_load_dwordx4 v[104:107], v[102:103], off offset:16
	s_waitcnt vmcnt(3)
	v_pk_add_f32 v[92:93], v[92:93], 1.0 op_sel_hi:[1,0]
	v_pk_add_f32 v[90:91], v[90:91], 1.0 op_sel_hi:[1,0]
	s_waitcnt vmcnt(2)
	v_pk_add_f32 v[96:97], v[96:97], 1.0 op_sel_hi:[1,0]
	v_pk_add_f32 v[94:95], v[94:95], 1.0 op_sel_hi:[1,0]
	s_waitcnt vmcnt(1)
	v_pk_mul_f32 v[102:103], v[100:101], v[92:93]
	v_pk_mul_f32 v[100:101], v[98:99], v[90:91]
	s_waitcnt vmcnt(0)
	v_pk_mul_f32 v[98:99], v[106:107], v[96:97]
	v_pk_mul_f32 v[96:97], v[104:105], v[94:95]
